# GEMM epilogue stores made write-through (sc1) so the XCD-leader L2 writeback at each grid barrier has little left to flush
# baseline (speedup 1.0000x reference)
; __device__ __forceinline__ void tile_rstd(float (&rs)[2][4], const float* ssp, int rowtile, int wr, int fr, int fq) {
;     const int lane = fq * 16 + fr; f32x4 pa[2][4][2];
; #pragma unroll
;     for (int ai = 0; ai < 2; ++ai)
; #pragma unroll
;         for (int m = 0; m < 4; ++m) { const f32x4* p = (const f32x4*)(ssp + (size_t)(rowtile + wr * 64 + ai * HALF + m * 16 + (lane >> 2)) * 32 + (lane & 3) * 8); pa[ai][m][0] = p[0]; pa[ai][m][1] = p[1]; }
; #pragma unroll
;     for (int ai = 0; ai < 2; ++ai)
; #pragma unroll
;         for (int m = 0; m < 4; ++m) { const f32x4 a = pa[ai][m][0], b = pa[ai][m][1];
;             float t = ((a.x + a.y) + (a.z + a.w)) + ((b.x + b.y) + (b.z + b.w));
;             t += __shfl_xor(t, 1); t += __shfl_xor(t, 2);
;             rs[ai][m] = __shfl(rsqrtf(t * (1.0f / 2048.0f) + 1e-6f), fr * 4); }
;     __device__ __forceinline__ void operator()(const f32x4 (&acc)[2][2][4][2], const Unit& u, int wr, int wc, int fr, int fq) const {
;         const int row0 = u.pm * BM + wr * 64 + fr; const int col0 = u.pn * HALF + wc * 32 + 8 * fq;
;         float rsa[2][4]; tile_rstd(rsa, ss, u.pm * BM, wr, fr, fq);
.LBB0_420:
	s_lshl_b32 s0, s6, 8
	s_add_i32 s0, s0, s73
	v_or_b32_e32 v130, s0, v206
	v_ashrrev_i32_e32 v131, 31, v130
	v_lshlrev_b64 v[132:133], 7, v[130:131]
	v_lshl_add_u64 v[132:133], v[184:185], 0, v[132:133]
	global_load_dwordx4 v[232:235], v[132:133], off
	global_load_dwordx4 v[242:245], v[132:133], off offset:16
	v_or_b32_e32 v132, 16, v130
	v_ashrrev_i32_e32 v133, 31, v132
	v_lshlrev_b64 v[132:133], 7, v[132:133]
	v_lshl_add_u64 v[132:133], v[184:185], 0, v[132:133]
	global_load_dwordx4 v[246:249], v[132:133], off
	global_load_dwordx4 v[228:231], v[132:133], off offset:16
	v_or_b32_e32 v132, 32, v130
	v_ashrrev_i32_e32 v133, 31, v132
	v_lshlrev_b64 v[132:133], 7, v[132:133]
	v_lshl_add_u64 v[132:133], v[184:185], 0, v[132:133]
	global_load_dwordx4 v[170:173], v[132:133], off
	global_load_dwordx4 v[174:177], v[132:133], off offset:16
	v_or_b32_e32 v132, 48, v130
	v_ashrrev_i32_e32 v133, 31, v132
	v_lshlrev_b64 v[132:133], 7, v[132:133]
	v_lshl_add_u64 v[132:133], v[184:185], 0, v[132:133]
	global_load_dwordx4 v[166:169], v[132:133], off
	global_load_dwordx4 v[162:165], v[132:133], off offset:16
	v_add_u32_e32 v132, 0x80, v130
	v_ashrrev_i32_e32 v133, 31, v132
	v_lshlrev_b64 v[132:133], 7, v[132:133]
	v_lshl_add_u64 v[132:133], v[184:185], 0, v[132:133]
	global_load_dwordx4 v[158:161], v[132:133], off
	global_load_dwordx4 v[154:157], v[132:133], off offset:16
	v_add_u32_e32 v132, 0x90, v130
	v_ashrrev_i32_e32 v133, 31, v132
	v_lshlrev_b64 v[132:133], 7, v[132:133]
	v_lshl_add_u64 v[132:133], v[184:185], 0, v[132:133]
	global_load_dwordx4 v[150:153], v[132:133], off
	global_load_dwordx4 v[146:149], v[132:133], off offset:16
	v_add_u32_e32 v132, 0xa0, v130
	v_ashrrev_i32_e32 v133, 31, v132
	v_lshlrev_b64 v[132:133], 7, v[132:133]
	v_add_u32_e32 v130, 0xb0, v130
	v_lshl_add_u64 v[132:133], v[184:185], 0, v[132:133]
	v_ashrrev_i32_e32 v131, 31, v130
	global_load_dwordx4 v[142:145], v[132:133], off
	global_load_dwordx4 v[138:141], v[132:133], off offset:16
	v_lshlrev_b64 v[130:131], 7, v[130:131]
	v_lshl_add_u64 v[130:131], v[184:185], 0, v[130:131]
	global_load_dwordx4 v[134:137], v[130:131], off
	s_nop 0
	global_load_dwordx4 v[130:133], v[130:131], off offset:16
	v_and_b32_e32 v192, 64, v220
	v_xor_b32_e32 v191, 1, v220
	v_add_u32_e32 v192, 64, v192
	v_cmp_lt_i32_e32 vcc, v191, v192
	v_or_b32_e32 v210, s0, v193
	v_readlane_b32 s0, v254, 63
	v_cndmask_b32_e32 v191, v220, v191, vcc
	v_lshlrev_b32_e32 v212, 2, v191
	v_xor_b32_e32 v191, 2, v220
	v_cmp_lt_i32_e32 vcc, v191, v192
	v_lshl_or_b32 v190, s2, 7, v208
	v_readlane_b32 s1, v255, 0
	v_cndmask_b32_e32 v191, v220, v191, vcc
	v_lshlrev_b32_e32 v211, 2, v191
	v_lshlrev_b32_e32 v191, 2, v220
	v_and_or_b32 v191, v191, s25, v207
	s_movk_i32 s2, 0x2c00
	s_waitcnt vmcnt(0) lgkmcnt(0)
	v_mov_b32_e32 v204, v232
	v_mov_b32_e32 v205, v242
	v_mov_b32_e32 v242, v233
	v_mov_b32_e32 v214, v234
	v_mov_b32_e32 v215, v244
	v_mov_b32_e32 v244, v235
	v_pk_add_f32 v[204:205], v[204:205], v[242:243]
	v_pk_add_f32 v[214:215], v[214:215], v[244:245]
	s_nop 0
	v_pk_add_f32 v[204:205], v[204:205], v[214:215]
	v_mov_b32_e32 v214, v246
	v_mov_b32_e32 v215, v228
	v_mov_b32_e32 v228, v247
	v_pk_add_f32 v[214:215], v[214:215], v[228:229]
	v_mov_b32_e32 v228, v248
	v_mov_b32_e32 v229, v230
	v_mov_b32_e32 v230, v249
	v_pk_add_f32 v[228:229], v[228:229], v[230:231]
	s_nop 0
	v_pk_add_f32 v[214:215], v[214:215], v[228:229]
	v_mov_b32_e32 v229, v204
	v_mov_b32_e32 v228, v214
	v_mov_b32_e32 v204, v215
	v_pk_add_f32 v[204:205], v[228:229], v[204:205]
	ds_bpermute_b32 v215, v212, v205
	ds_bpermute_b32 v214, v212, v204
	s_waitcnt lgkmcnt(0)
	v_pk_add_f32 v[204:205], v[204:205], v[214:215]
	ds_bpermute_b32 v215, v211, v205
	ds_bpermute_b32 v214, v211, v204
	s_waitcnt lgkmcnt(0)
	v_pk_add_f32 v[214:215], v[204:205], v[214:215]
	v_mov_b64_e32 v[204:205], s[24:25]
	v_pk_fma_f32 v[214:215], v[214:215], s[18:19], v[204:205] op_sel_hi:[1,0,0]
	s_nop 0
	v_mul_f32_e32 v192, 0x4b800000, v215
	v_cmp_gt_f32_e64 s[40:41], s12, v215
	v_cmp_gt_f32_e32 vcc, s12, v214
	s_nop 0
	v_cndmask_b32_e64 v192, v215, v192, s[40:41]
	v_rsq_f32_e32 v192, v192
	v_mov_b32_e32 v215, v174
	v_mov_b32_e32 v174, v171
	v_mul_f32_e32 v202, 0x45800000, v192
	v_cndmask_b32_e64 v192, v192, v202, s[40:41]
	ds_bpermute_b32 v202, v191, v192
	v_mul_f32_e32 v192, 0x4b800000, v214
	v_cndmask_b32_e32 v192, v214, v192, vcc
	v_mov_b32_e32 v214, v170
	v_pk_add_f32 v[170:171], v[214:215], v[174:175]
	v_mov_b32_e32 v174, v172
	v_mov_b32_e32 v175, v176
	v_mov_b32_e32 v176, v173
	v_pk_add_f32 v[172:173], v[174:175], v[176:177]
	s_waitcnt lgkmcnt(0)
; __device__ __forceinline__ unsigned pk_bf16(float lo, float hi) { f32x2e v = {lo, hi}; bf16x2e b = __builtin_convertvector(v, bf16x2e); return __builtin_bit_cast(unsigned, b); }
; __device__ __forceinline__ float silu_mul(float g, float u) { return g * __builtin_amdgcn_rcpf(1.0f + __builtin_amdgcn_exp2f(-1.4426950408889634f * g)) * u; }
; __device__ __forceinline__ void tile_rstd(float (&rs)[2][4], const float* ssp, int rowtile, int wr, int fr, int fq) {
;     ...
;         for (int m = 0; m < 4; ++m) { const f32x4 a = pa[ai][m][0], b = pa[ai][m][1];
;             float t = ((a.x + a.y) + (a.z + a.w)) + ((b.x + b.y) + (b.z + b.w));
;             t += __shfl_xor(t, 1); t += __shfl_xor(t, 2);
;             rs[ai][m] = __shfl(rsqrtf(t * (1.0f / 2048.0f) + 1e-6f), fr * 4); }
;     __device__ __forceinline__ void operator()(const f32x4 (&acc)[2][2][4][2], const Unit& u, int wr, int wc, int fr, int fq) const {
;     ...
;             for (int m = 0; m < 4; ++m) { bf16_t* rowp = O + (size_t)(row0 + ai * HALF + m * 16) * ldc + col0;
;                 const float rs = rsa[ai][m];
;                 const f32x4 g0 = acc[ai][0][m][0] * rs, g1 = acc[ai][0][m][1] * rs, u0 = acc[ai][1][m][0] * rs, u1 = acc[ai][1][m][1] * rs;
;                 u32x4 w; w.x = pk_bf16(silu_mul(g0[0], u0[0]), silu_mul(g0[1], u0[1])); w.y = pk_bf16(silu_mul(g0[2], u0[2]), silu_mul(g0[3], u0[3]));
;                 w.z = pk_bf16(silu_mul(g1[0], u1[0]), silu_mul(g1[1], u1[1])); w.w = pk_bf16(silu_mul(g1[2], u1[2]), silu_mul(g1[3], u1[3]));
	v_pk_mul_f32 v[126:127], v[126:127], v[202:203] op_sel_hi:[1,0]
	v_pk_add_f32 v[170:171], v[170:171], v[172:173]
	v_mov_b32_e32 v172, v166
	v_mov_b32_e32 v173, v162
	v_mov_b32_e32 v162, v167
	v_mov_b32_e32 v166, v168
	v_mov_b32_e32 v167, v164
	v_mov_b32_e32 v164, v169
	v_pk_add_f32 v[164:165], v[166:167], v[164:165]
	v_mov_b32_e32 v166, v158
	v_mov_b32_e32 v167, v154
	v_mov_b32_e32 v154, v159
	v_mov_b32_e32 v158, v160
	v_mov_b32_e32 v159, v156
	v_mov_b32_e32 v156, v161
	v_pk_add_f32 v[154:155], v[166:167], v[154:155]
	v_pk_add_f32 v[156:157], v[158:159], v[156:157]
	v_pk_mul_f32 v[118:119], v[118:119], v[202:203] op_sel_hi:[1,0]
	v_pk_add_f32 v[154:155], v[154:155], v[156:157]
	v_mov_b32_e32 v156, v150
	v_mov_b32_e32 v157, v146
	v_mov_b32_e32 v146, v151
	v_mov_b32_e32 v150, v152
	v_mov_b32_e32 v151, v148
	v_mov_b32_e32 v148, v153
	v_pk_add_f32 v[148:149], v[150:151], v[148:149]
	v_mov_b32_e32 v150, v142
	v_mov_b32_e32 v151, v138
	v_mov_b32_e32 v138, v143
	v_mov_b32_e32 v142, v144
	v_mov_b32_e32 v143, v140
	v_mov_b32_e32 v140, v145
	v_pk_add_f32 v[138:139], v[150:151], v[138:139]
	v_pk_add_f32 v[140:141], v[142:143], v[140:141]
	v_pk_add_f32 v[162:163], v[172:173], v[162:163]
	v_pk_add_f32 v[138:139], v[138:139], v[140:141]
	v_mov_b32_e32 v140, v134
	v_mov_b32_e32 v141, v130
	v_mov_b32_e32 v130, v135
	v_pk_add_f32 v[130:131], v[140:141], v[130:131]
	v_pk_mul_f32 v[140:141], v[116:117], v[202:203] op_sel_hi:[1,0]
	v_pk_mul_f32 v[116:117], v[114:115], v[202:203] op_sel_hi:[1,0]
	v_mul_f32_e32 v114, 0xbfb8aa3b, v126
	v_mul_f32_e32 v115, 0xbfb8aa3b, v127
	v_exp_f32_e32 v114, v114
	v_exp_f32_e32 v115, v115
	v_pk_mul_f32 v[128:129], v[128:129], v[202:203] op_sel_hi:[1,0]
	v_pk_add_f32 v[162:163], v[162:163], v[164:165]
	v_add_f32_e32 v114, 1.0, v114
	v_add_f32_e32 v115, 1.0, v115
	v_rcp_f32_e32 v114, v114
	v_rcp_f32_e32 v115, v115
	v_mov_b32_e32 v164, v162
	v_mov_b32_e32 v165, v170
	v_mov_b32_e32 v170, v163
	v_pk_mul_f32 v[114:115], v[126:127], v[114:115]
	v_pk_add_f32 v[162:163], v[164:165], v[170:171]
	v_pk_mul_f32 v[114:115], v[118:119], v[114:115]
	ds_bpermute_b32 v165, v212, v163
	v_cvt_pk_bf16_f32 v114, v114, v115
	v_mul_f32_e32 v115, 0xbfb8aa3b, v128
	v_exp_f32_e32 v115, v115
	ds_bpermute_b32 v164, v212, v162
	v_pk_add_f32 v[146:147], v[156:157], v[146:147]
	v_mov_b32_e32 v134, v136
	v_add_f32_e32 v115, 1.0, v115
	v_rcp_f32_e32 v118, v115
	v_mul_f32_e32 v115, 0xbfb8aa3b, v129
	v_pk_add_f32 v[146:147], v[146:147], v[148:149]
	v_exp_f32_e32 v115, v115
	s_waitcnt lgkmcnt(0)
	v_pk_add_f32 v[162:163], v[162:163], v[164:165]
	v_mov_b32_e32 v148, v146
	v_mov_b32_e32 v149, v154
	v_mov_b32_e32 v154, v147
	ds_bpermute_b32 v165, v211, v163
	ds_bpermute_b32 v164, v211, v162
	v_pk_add_f32 v[146:147], v[148:149], v[154:155]
	ds_bpermute_b32 v149, v212, v147
	ds_bpermute_b32 v148, v212, v146
	v_add_f32_e32 v115, 1.0, v115
	v_mov_b32_e32 v135, v132
	v_mov_b32_e32 v132, v137
	v_rcp_f32_e32 v119, v115
	v_pk_add_f32 v[132:133], v[134:135], v[132:133]
	s_waitcnt lgkmcnt(2)
	v_pk_add_f32 v[162:163], v[162:163], v[164:165]
	v_pk_add_f32 v[130:131], v[130:131], v[132:133]
	v_pk_fma_f32 v[162:163], v[162:163], s[18:19], v[204:205] op_sel_hi:[1,0,0]
	s_waitcnt lgkmcnt(0)
	v_pk_add_f32 v[146:147], v[146:147], v[148:149]
	v_mov_b32_e32 v132, v130
	v_mov_b32_e32 v133, v138
	v_mov_b32_e32 v138, v131
	v_mul_f32_e32 v164, 0x4b800000, v163
	v_cmp_gt_f32_e64 s[40:41], s12, v163
	ds_bpermute_b32 v149, v211, v147
	ds_bpermute_b32 v148, v211, v146
	v_pk_add_f32 v[130:131], v[132:133], v[138:139]
	v_pk_mul_f32 v[120:121], v[120:121], v[202:203] op_sel_hi:[1,0]
	v_pk_mul_f32 v[118:119], v[128:129], v[118:119]
	v_cndmask_b32_e64 v163, v163, v164, s[40:41]
	ds_bpermute_b32 v133, v212, v131
	ds_bpermute_b32 v132, v212, v130
	v_pk_mul_f32 v[122:123], v[122:123], v[202:203] op_sel_hi:[1,0]
	v_pk_mul_f32 v[118:119], v[120:121], v[118:119]
	v_rsq_f32_e32 v163, v163
	v_cvt_pk_bf16_f32 v115, v118, v119
	v_mul_f32_e32 v118, 0xbfb8aa3b, v122
	v_mul_f32_e32 v119, 0xbfb8aa3b, v123
	v_rsq_f32_e32 v192, v192
	v_exp_f32_e32 v118, v118
	v_exp_f32_e32 v119, v119
	s_waitcnt lgkmcnt(2)
	v_pk_add_f32 v[146:147], v[146:147], v[148:149]
	v_mul_f32_e32 v164, 0x45800000, v163
	v_pk_fma_f32 v[146:147], v[146:147], s[18:19], v[204:205] op_sel_hi:[1,0,0]
	s_waitcnt lgkmcnt(0)
	v_pk_add_f32 v[130:131], v[130:131], v[132:133]
	v_mul_f32_e32 v213, 0x45800000, v192
	v_cndmask_b32_e64 v163, v163, v164, s[40:41]
	v_mul_f32_e32 v148, 0x4b800000, v147
	v_cmp_gt_f32_e64 s[40:41], s12, v147
	ds_bpermute_b32 v133, v211, v131
	ds_bpermute_b32 v132, v211, v130
	v_add_f32_e32 v118, 1.0, v118
	v_add_f32_e32 v119, 1.0, v119
	v_cndmask_b32_e32 v192, v192, v213, vcc
	v_cmp_gt_f32_e32 vcc, s12, v162
	ds_bpermute_b32 v164, v191, v163
	v_mul_f32_e32 v163, 0x4b800000, v162
	v_cndmask_b32_e64 v147, v147, v148, s[40:41]
	v_rcp_f32_e32 v118, v118
	v_rcp_f32_e32 v119, v119
	v_cndmask_b32_e32 v162, v162, v163, vcc
	v_rsq_f32_e32 v147, v147
	v_rsq_f32_e32 v162, v162
	s_waitcnt lgkmcnt(1)
; __device__ __forceinline__ unsigned pk_bf16(float lo, float hi) { f32x2e v = {lo, hi}; bf16x2e b = __builtin_convertvector(v, bf16x2e); return __builtin_bit_cast(unsigned, b); }
; __device__ __forceinline__ float silu_mul(float g, float u) { return g * __builtin_amdgcn_rcpf(1.0f + __builtin_amdgcn_exp2f(-1.4426950408889634f * g)) * u; }
;     __device__ __forceinline__ void operator()(const f32x4 (&acc)[2][2][4][2], const Unit& u, int wr, int wc, int fr, int fq) const {
;     ...
;             for (int m = 0; m < 4; ++m) { bf16_t* rowp = O + (size_t)(row0 + ai * HALF + m * 16) * ldc + col0;
;                 const float rs = rsa[ai][m];
;                 const f32x4 g0 = acc[ai][0][m][0] * rs, g1 = acc[ai][0][m][1] * rs, u0 = acc[ai][1][m][0] * rs, u1 = acc[ai][1][m][1] * rs;
;                 u32x4 w; w.x = pk_bf16(silu_mul(g0[0], u0[0]), silu_mul(g0[1], u0[1])); w.y = pk_bf16(silu_mul(g0[2], u0[2]), silu_mul(g0[3], u0[3]));
;                 w.z = pk_bf16(silu_mul(g1[0], u1[0]), silu_mul(g1[1], u1[1])); w.w = pk_bf16(silu_mul(g1[2], u1[2]), silu_mul(g1[3], u1[3]));
;                 *(u32x4*)rowp = w; }
	v_pk_add_f32 v[130:131], v[130:131], v[132:133]
	v_pk_mul_f32 v[118:119], v[122:123], v[118:119]
	v_mul_f32_e32 v148, 0x45800000, v147
	v_pk_fma_f32 v[130:131], v[130:131], s[18:19], v[204:205] op_sel_hi:[1,0,0]
	v_pk_mul_f32 v[124:125], v[124:125], v[202:203] op_sel_hi:[1,0]
	v_pk_mul_f32 v[116:117], v[116:117], v[118:119]
	v_mul_f32_e32 v163, 0x45800000, v162
	v_cndmask_b32_e64 v147, v147, v148, s[40:41]
	v_mul_f32_e32 v132, 0x4b800000, v131
	v_cmp_gt_f32_e64 s[40:41], s12, v131
	v_cvt_pk_bf16_f32 v116, v116, v117
	v_mul_f32_e32 v117, 0xbfb8aa3b, v124
	v_cndmask_b32_e32 v162, v162, v163, vcc
	v_cmp_gt_f32_e32 vcc, s12, v146
	ds_bpermute_b32 v148, v191, v147
	v_mul_f32_e32 v147, 0x4b800000, v146
	v_cndmask_b32_e64 v131, v131, v132, s[40:41]
	v_exp_f32_e32 v117, v117
	v_cndmask_b32_e32 v146, v146, v147, vcc
	v_rsq_f32_e32 v131, v131
	v_rsq_f32_e32 v146, v146
	v_add_f32_e32 v117, 1.0, v117
	v_rcp_f32_e32 v118, v117
	v_mul_f32_e32 v132, 0x45800000, v131
	v_mul_f32_e32 v117, 0xbfb8aa3b, v125
	v_mul_f32_e32 v147, 0x45800000, v146
	v_cndmask_b32_e64 v131, v131, v132, s[40:41]
	v_exp_f32_e32 v117, v117
	v_cndmask_b32_e32 v146, v146, v147, vcc
	v_cmp_gt_f32_e32 vcc, s12, v130
	ds_bpermute_b32 v136, v191, v131
	v_mul_f32_e32 v131, 0x4b800000, v130
	v_cndmask_b32_e32 v130, v130, v131, vcc
	v_rsq_f32_e32 v130, v130
	v_add_f32_e32 v117, 1.0, v117
	v_rcp_f32_e32 v119, v117
	ds_bpermute_b32 v192, v191, v192
	v_mul_f32_e32 v131, 0x45800000, v130
	v_cndmask_b32_e32 v130, v130, v131, vcc
	ds_bpermute_b32 v162, v191, v162
	ds_bpermute_b32 v146, v191, v146
	ds_bpermute_b32 v130, v191, v130
	v_ashrrev_i32_e32 v191, 31, v190
	v_mov_b64_e32 v[132:133], s[0:1]
	v_pk_mul_f32 v[118:119], v[124:125], v[118:119]
	v_mad_i64_i32 v[138:139], s[0:1], v210, s2, v[132:133]
	v_lshlrev_b64 v[134:135], 1, v[190:191]
	v_pk_mul_f32 v[118:119], v[140:141], v[118:119]
	v_lshl_add_u64 v[138:139], v[138:139], 0, v[134:135]
	v_cvt_pk_bf16_f32 v117, v118, v119
	s_waitcnt lgkmcnt(3)
	v_pk_mul_f32 v[110:111], v[110:111], v[192:193] op_sel_hi:[1,0]
	global_store_dwordx4 v[138:139], v[114:117], off sc1
	v_pk_mul_f32 v[102:103], v[102:103], v[192:193] op_sel_hi:[1,0]
	v_pk_mul_f32 v[112:113], v[112:113], v[192:193] op_sel_hi:[1,0]
	v_pk_mul_f32 v[116:117], v[100:101], v[192:193] op_sel_hi:[1,0]
	v_pk_mul_f32 v[100:101], v[98:99], v[192:193] op_sel_hi:[1,0]
	v_mul_f32_e32 v98, 0xbfb8aa3b, v110
	v_mul_f32_e32 v99, 0xbfb8aa3b, v111
	v_exp_f32_e32 v98, v98
	v_exp_f32_e32 v99, v99
	v_pk_mul_f32 v[104:105], v[104:105], v[192:193] op_sel_hi:[1,0]
	v_pk_mul_f32 v[106:107], v[106:107], v[192:193] op_sel_hi:[1,0]
	v_add_f32_e32 v98, 1.0, v98
	v_add_f32_e32 v99, 1.0, v99
	v_rcp_f32_e32 v98, v98
	v_rcp_f32_e32 v99, v99
	v_pk_mul_f32 v[108:109], v[108:109], v[192:193] op_sel_hi:[1,0]
	v_or_b32_e32 v114, 16, v210
	v_mad_i64_i32 v[114:115], s[0:1], v114, s2, v[132:133]
	v_pk_mul_f32 v[98:99], v[110:111], v[98:99]
	v_lshl_add_u64 v[114:115], v[114:115], 0, v[134:135]
	v_pk_mul_f32 v[98:99], v[102:103], v[98:99]
	v_pk_mul_f32 v[92:93], v[92:93], v[164:165] op_sel_hi:[1,0]
	v_cvt_pk_bf16_f32 v98, v98, v99
	v_mul_f32_e32 v99, 0xbfb8aa3b, v112
	v_exp_f32_e32 v99, v99
	v_pk_mul_f32 v[84:85], v[84:85], v[164:165] op_sel_hi:[1,0]
	v_pk_mul_f32 v[94:95], v[94:95], v[164:165] op_sel_hi:[1,0]
	v_pk_mul_f32 v[86:87], v[86:87], v[164:165] op_sel_hi:[1,0]
	v_add_f32_e32 v99, 1.0, v99
	v_rcp_f32_e32 v102, v99
	v_mul_f32_e32 v99, 0xbfb8aa3b, v113
	v_exp_f32_e32 v99, v99
	v_pk_mul_f32 v[88:89], v[88:89], v[164:165] op_sel_hi:[1,0]
	v_pk_mul_f32 v[90:91], v[90:91], v[164:165] op_sel_hi:[1,0]
	s_waitcnt lgkmcnt(0)
	v_pk_mul_f32 v[76:77], v[76:77], v[162:163] op_sel_hi:[1,0]
	v_add_f32_e32 v99, 1.0, v99
	v_rcp_f32_e32 v103, v99
	v_pk_mul_f32 v[68:69], v[68:69], v[162:163] op_sel_hi:[1,0]
	v_pk_mul_f32 v[78:79], v[78:79], v[162:163] op_sel_hi:[1,0]
	v_pk_mul_f32 v[70:71], v[70:71], v[162:163] op_sel_hi:[1,0]
	v_pk_mul_f32 v[102:103], v[112:113], v[102:103]
	v_pk_mul_f32 v[72:73], v[72:73], v[162:163] op_sel_hi:[1,0]
	v_pk_mul_f32 v[102:103], v[104:105], v[102:103]
	v_pk_mul_f32 v[74:75], v[74:75], v[162:163] op_sel_hi:[1,0]
	v_cvt_pk_bf16_f32 v99, v102, v103
	v_mul_f32_e32 v102, 0xbfb8aa3b, v106
	v_mul_f32_e32 v103, 0xbfb8aa3b, v107
	v_exp_f32_e32 v102, v102
	v_exp_f32_e32 v103, v103
	v_pk_mul_f32 v[60:61], v[60:61], v[148:149] op_sel_hi:[1,0]
	v_pk_mul_f32 v[52:53], v[52:53], v[148:149] op_sel_hi:[1,0]
	v_add_f32_e32 v102, 1.0, v102
	v_add_f32_e32 v103, 1.0, v103
	v_rcp_f32_e32 v102, v102
	v_rcp_f32_e32 v103, v103
	v_pk_mul_f32 v[62:63], v[62:63], v[148:149] op_sel_hi:[1,0]
	v_pk_mul_f32 v[54:55], v[54:55], v[148:149] op_sel_hi:[1,0]
	v_pk_mul_f32 v[56:57], v[56:57], v[148:149] op_sel_hi:[1,0]
	v_pk_mul_f32 v[102:103], v[106:107], v[102:103]
	v_pk_mul_f32 v[58:59], v[58:59], v[148:149] op_sel_hi:[1,0]
	v_pk_mul_f32 v[100:101], v[100:101], v[102:103]
	v_pk_mul_f32 v[44:45], v[44:45], v[146:147] op_sel_hi:[1,0]
	v_cvt_pk_bf16_f32 v100, v100, v101
	v_mul_f32_e32 v101, 0xbfb8aa3b, v108
	v_exp_f32_e32 v101, v101
	v_pk_mul_f32 v[36:37], v[36:37], v[146:147] op_sel_hi:[1,0]
	v_pk_mul_f32 v[46:47], v[46:47], v[146:147] op_sel_hi:[1,0]
	v_pk_mul_f32 v[38:39], v[38:39], v[146:147] op_sel_hi:[1,0]
	v_add_f32_e32 v101, 1.0, v101
	v_rcp_f32_e32 v102, v101
	v_mul_f32_e32 v101, 0xbfb8aa3b, v109
	v_exp_f32_e32 v101, v101
	v_pk_mul_f32 v[40:41], v[40:41], v[146:147] op_sel_hi:[1,0]
	v_pk_mul_f32 v[42:43], v[42:43], v[146:147] op_sel_hi:[1,0]
	v_pk_mul_f32 v[28:29], v[28:29], v[136:137] op_sel_hi:[1,0]
	v_add_f32_e32 v101, 1.0, v101
	v_rcp_f32_e32 v103, v101
	v_pk_mul_f32 v[20:21], v[20:21], v[136:137] op_sel_hi:[1,0]
; __device__ __forceinline__ unsigned pk_bf16(float lo, float hi) { f32x2e v = {lo, hi}; bf16x2e b = __builtin_convertvector(v, bf16x2e); return __builtin_bit_cast(unsigned, b); }
; __device__ __forceinline__ float silu_mul(float g, float u) { return g * __builtin_amdgcn_rcpf(1.0f + __builtin_amdgcn_exp2f(-1.4426950408889634f * g)) * u; }
;     __device__ __forceinline__ void operator()(const f32x4 (&acc)[2][2][4][2], const Unit& u, int wr, int wc, int fr, int fq) const {
;     ...
;             for (int m = 0; m < 4; ++m) { bf16_t* rowp = O + (size_t)(row0 + ai * HALF + m * 16) * ldc + col0;
;                 const float rs = rsa[ai][m];
;                 const f32x4 g0 = acc[ai][0][m][0] * rs, g1 = acc[ai][0][m][1] * rs, u0 = acc[ai][1][m][0] * rs, u1 = acc[ai][1][m][1] * rs;
;                 u32x4 w; w.x = pk_bf16(silu_mul(g0[0], u0[0]), silu_mul(g0[1], u0[1])); w.y = pk_bf16(silu_mul(g0[2], u0[2]), silu_mul(g0[3], u0[3]));
;                 w.z = pk_bf16(silu_mul(g1[0], u1[0]), silu_mul(g1[1], u1[1])); w.w = pk_bf16(silu_mul(g1[2], u1[2]), silu_mul(g1[3], u1[3]));
;                 *(u32x4*)rowp = w; }
	v_pk_mul_f32 v[30:31], v[30:31], v[136:137] op_sel_hi:[1,0]
	v_pk_mul_f32 v[22:23], v[22:23], v[136:137] op_sel_hi:[1,0]
	v_pk_mul_f32 v[102:103], v[108:109], v[102:103]
	v_pk_mul_f32 v[24:25], v[24:25], v[136:137] op_sel_hi:[1,0]
	v_pk_mul_f32 v[102:103], v[116:117], v[102:103]
	v_pk_mul_f32 v[26:27], v[26:27], v[136:137] op_sel_hi:[1,0]
	v_cvt_pk_bf16_f32 v101, v102, v103
	global_store_dwordx4 v[114:115], v[98:101], off sc1
	v_pk_mul_f32 v[12:13], v[12:13], v[130:131] op_sel_hi:[1,0]
	v_pk_mul_f32 v[4:5], v[4:5], v[130:131] op_sel_hi:[1,0]
	v_pk_mul_f32 v[100:101], v[82:83], v[164:165] op_sel_hi:[1,0]
	v_pk_mul_f32 v[82:83], v[80:81], v[164:165] op_sel_hi:[1,0]
	v_mul_f32_e32 v80, 0xbfb8aa3b, v92
	v_mul_f32_e32 v81, 0xbfb8aa3b, v93
	v_exp_f32_e32 v80, v80
	v_exp_f32_e32 v81, v81
	v_or_b32_e32 v98, 32, v210
	v_mad_i64_i32 v[98:99], s[0:1], v98, s2, v[132:133]
	v_add_f32_e32 v80, 1.0, v80
	v_add_f32_e32 v81, 1.0, v81
	v_rcp_f32_e32 v80, v80
	v_rcp_f32_e32 v81, v81
	v_lshl_add_u64 v[98:99], v[98:99], 0, v[134:135]
	v_pk_mul_f32 v[14:15], v[14:15], v[130:131] op_sel_hi:[1,0]
	v_pk_mul_f32 v[6:7], v[6:7], v[130:131] op_sel_hi:[1,0]
	v_pk_mul_f32 v[80:81], v[92:93], v[80:81]
	v_pk_mul_f32 v[8:9], v[8:9], v[130:131] op_sel_hi:[1,0]
	v_pk_mul_f32 v[80:81], v[84:85], v[80:81]
	v_pk_mul_f32 v[10:11], v[10:11], v[130:131] op_sel_hi:[1,0]
	v_cvt_pk_bf16_f32 v80, v80, v81
	v_mul_f32_e32 v81, 0xbfb8aa3b, v94
	v_exp_f32_e32 v81, v81
	s_andn2_b64 vcc, exec, s[38:39]
	v_add_f32_e32 v81, 1.0, v81
	v_rcp_f32_e32 v84, v81
	v_mul_f32_e32 v81, 0xbfb8aa3b, v95
	v_exp_f32_e32 v81, v81
	s_nop 0
	v_add_f32_e32 v81, 1.0, v81
	v_rcp_f32_e32 v85, v81
	s_nop 0
	v_pk_mul_f32 v[84:85], v[94:95], v[84:85]
	s_nop 0
	v_pk_mul_f32 v[84:85], v[86:87], v[84:85]
	s_nop 0
	v_cvt_pk_bf16_f32 v81, v84, v85
	v_mul_f32_e32 v84, 0xbfb8aa3b, v88
	v_mul_f32_e32 v85, 0xbfb8aa3b, v89
	v_exp_f32_e32 v84, v84
	v_exp_f32_e32 v85, v85
	v_add_f32_e32 v84, 1.0, v84
	v_add_f32_e32 v85, 1.0, v85
	v_rcp_f32_e32 v84, v84
	v_rcp_f32_e32 v85, v85
	s_nop 0
	v_pk_mul_f32 v[84:85], v[88:89], v[84:85]
	s_nop 0
	v_pk_mul_f32 v[82:83], v[82:83], v[84:85]
	s_nop 0
	v_cvt_pk_bf16_f32 v82, v82, v83
	v_mul_f32_e32 v83, 0xbfb8aa3b, v90
	v_exp_f32_e32 v83, v83
	s_nop 0
	v_add_f32_e32 v83, 1.0, v83
	v_rcp_f32_e32 v84, v83
	v_mul_f32_e32 v83, 0xbfb8aa3b, v91
	v_exp_f32_e32 v83, v83
	s_nop 0
	v_add_f32_e32 v83, 1.0, v83
	v_rcp_f32_e32 v85, v83
	s_nop 0
	v_pk_mul_f32 v[84:85], v[90:91], v[84:85]
	s_nop 0
	v_pk_mul_f32 v[84:85], v[100:101], v[84:85]
	s_nop 0
	v_cvt_pk_bf16_f32 v83, v84, v85
	global_store_dwordx4 v[98:99], v[80:83], off sc1
	s_nop 1
	v_pk_mul_f32 v[82:83], v[66:67], v[162:163] op_sel_hi:[1,0]
	v_pk_mul_f32 v[66:67], v[64:65], v[162:163] op_sel_hi:[1,0]
	v_mul_f32_e32 v64, 0xbfb8aa3b, v76
	v_mul_f32_e32 v65, 0xbfb8aa3b, v77
	v_exp_f32_e32 v64, v64
	v_exp_f32_e32 v65, v65
	v_or_b32_e32 v80, 48, v210
	v_mad_i64_i32 v[80:81], s[0:1], v80, s2, v[132:133]
	v_add_f32_e32 v64, 1.0, v64
	v_add_f32_e32 v65, 1.0, v65
	v_rcp_f32_e32 v64, v64
	v_rcp_f32_e32 v65, v65
	v_lshl_add_u64 v[80:81], v[80:81], 0, v[134:135]
	v_pk_mul_f32 v[64:65], v[76:77], v[64:65]
	s_nop 0
	v_pk_mul_f32 v[64:65], v[68:69], v[64:65]
	s_nop 0
	v_cvt_pk_bf16_f32 v64, v64, v65
	v_mul_f32_e32 v65, 0xbfb8aa3b, v78
	v_exp_f32_e32 v65, v65
	s_nop 0
	v_add_f32_e32 v65, 1.0, v65
	v_rcp_f32_e32 v68, v65
	v_mul_f32_e32 v65, 0xbfb8aa3b, v79
	v_exp_f32_e32 v65, v65
	s_nop 0
	v_add_f32_e32 v65, 1.0, v65
	v_rcp_f32_e32 v69, v65
	s_nop 0
	v_pk_mul_f32 v[68:69], v[78:79], v[68:69]
	s_nop 0
	v_pk_mul_f32 v[68:69], v[70:71], v[68:69]
	s_nop 0
	v_cvt_pk_bf16_f32 v65, v68, v69
	v_mul_f32_e32 v68, 0xbfb8aa3b, v72
	v_mul_f32_e32 v69, 0xbfb8aa3b, v73
	v_exp_f32_e32 v68, v68
	v_exp_f32_e32 v69, v69
	v_add_f32_e32 v68, 1.0, v68
	v_add_f32_e32 v69, 1.0, v69
	v_rcp_f32_e32 v68, v68
	v_rcp_f32_e32 v69, v69
	s_nop 0
	v_pk_mul_f32 v[68:69], v[72:73], v[68:69]
	s_nop 0
	v_pk_mul_f32 v[66:67], v[66:67], v[68:69]
	s_nop 0
	v_cvt_pk_bf16_f32 v66, v66, v67
	v_mul_f32_e32 v67, 0xbfb8aa3b, v74
	v_exp_f32_e32 v67, v67
	s_nop 0
	v_add_f32_e32 v67, 1.0, v67
	v_rcp_f32_e32 v68, v67
	v_mul_f32_e32 v67, 0xbfb8aa3b, v75
	v_exp_f32_e32 v67, v67
	s_nop 0
	v_add_f32_e32 v67, 1.0, v67
	v_rcp_f32_e32 v69, v67
	s_nop 0
	v_pk_mul_f32 v[68:69], v[74:75], v[68:69]
	s_nop 0
	v_pk_mul_f32 v[68:69], v[82:83], v[68:69]
	s_nop 0
	v_cvt_pk_bf16_f32 v67, v68, v69
	global_store_dwordx4 v[80:81], v[64:67], off sc1
	s_nop 1
	v_pk_mul_f32 v[66:67], v[50:51], v[148:149] op_sel_hi:[1,0]
	v_pk_mul_f32 v[50:51], v[48:49], v[148:149] op_sel_hi:[1,0]
	v_mul_f32_e32 v48, 0xbfb8aa3b, v60
	v_mul_f32_e32 v49, 0xbfb8aa3b, v61
	v_exp_f32_e32 v48, v48
	v_exp_f32_e32 v49, v49
	v_add_u32_e32 v64, 0x80, v210
	v_mad_i64_i32 v[64:65], s[0:1], v64, s2, v[132:133]
	v_add_f32_e32 v48, 1.0, v48
	v_add_f32_e32 v49, 1.0, v49
	v_rcp_f32_e32 v48, v48
	v_rcp_f32_e32 v49, v49
	v_lshl_add_u64 v[64:65], v[64:65], 0, v[134:135]
	v_pk_mul_f32 v[48:49], v[60:61], v[48:49]
	s_nop 0
	v_pk_mul_f32 v[48:49], v[52:53], v[48:49]
	s_nop 0
	v_cvt_pk_bf16_f32 v48, v48, v49
	v_mul_f32_e32 v49, 0xbfb8aa3b, v62
	v_exp_f32_e32 v49, v49
	s_nop 0
	v_add_f32_e32 v49, 1.0, v49
	v_rcp_f32_e32 v52, v49
	v_mul_f32_e32 v49, 0xbfb8aa3b, v63
	v_exp_f32_e32 v49, v49
	s_nop 0
	v_add_f32_e32 v49, 1.0, v49
	v_rcp_f32_e32 v53, v49
	s_nop 0
	v_pk_mul_f32 v[52:53], v[62:63], v[52:53]
	s_nop 0
	v_pk_mul_f32 v[52:53], v[54:55], v[52:53]
	s_nop 0
	v_cvt_pk_bf16_f32 v49, v52, v53
	v_mul_f32_e32 v52, 0xbfb8aa3b, v56
	v_mul_f32_e32 v53, 0xbfb8aa3b, v57
	v_exp_f32_e32 v52, v52
	v_exp_f32_e32 v53, v53
	v_add_f32_e32 v52, 1.0, v52
	v_add_f32_e32 v53, 1.0, v53
; __device__ __forceinline__ unsigned pk_bf16(float lo, float hi) { f32x2e v = {lo, hi}; bf16x2e b = __builtin_convertvector(v, bf16x2e); return __builtin_bit_cast(unsigned, b); }
; __device__ __forceinline__ float silu_mul(float g, float u) { return g * __builtin_amdgcn_rcpf(1.0f + __builtin_amdgcn_exp2f(-1.4426950408889634f * g)) * u; }
; #define PG8_BAR __builtin_amdgcn_s_barrier()
;     __device__ __forceinline__ void operator()(const f32x4 (&acc)[2][2][4][2], const Unit& u, int wr, int wc, int fr, int fq) const {
;     ...
;             for (int m = 0; m < 4; ++m) { bf16_t* rowp = O + (size_t)(row0 + ai * HALF + m * 16) * ldc + col0;
;                 const float rs = rsa[ai][m];
;                 const f32x4 g0 = acc[ai][0][m][0] * rs, g1 = acc[ai][0][m][1] * rs, u0 = acc[ai][1][m][0] * rs, u1 = acc[ai][1][m][1] * rs;
;                 u32x4 w; w.x = pk_bf16(silu_mul(g0[0], u0[0]), silu_mul(g0[1], u0[1])); w.y = pk_bf16(silu_mul(g0[2], u0[2]), silu_mul(g0[3], u0[3]));
;                 w.z = pk_bf16(silu_mul(g1[0], u1[0]), silu_mul(g1[1], u1[1])); w.w = pk_bf16(silu_mul(g1[2], u1[2]), silu_mul(g1[3], u1[3]));
;                 *(u32x4*)rowp = w; }
; template <class Epi, class Sched, bool ALIGN_EPI = false, bool SP2 = false>
; __device__ __forceinline__ void gemm_phase(PG8_LAS unsigned char* lds, const Gemm g, const Sched& S, const Epi& E) {
;     ...
;         if (!has_next) break;
; #pragma unroll
;         for (int a = 0; a < 2; ++a)
; #pragma unroll
;             for (int b = 0; b < 2; ++b)
; #pragma unroll
;                 for (int m = 0; m < 4; ++m)
; #pragma unroll
;                     for (int n = 0; n < 2; ++n) acc[a][b][m][n] = (f32x4){0.f, 0.f, 0.f, 0.f};
;         cur = nxt; cA = nA; cB = nB; ++ui;
;         if constexpr (ALIGN_EPI) { if (wr == 1) PG8_BAR; }
	v_rcp_f32_e32 v52, v52
	v_rcp_f32_e32 v53, v53
	s_nop 0
	v_pk_mul_f32 v[52:53], v[56:57], v[52:53]
	s_nop 0
	v_pk_mul_f32 v[50:51], v[50:51], v[52:53]
	s_nop 0
	v_cvt_pk_bf16_f32 v50, v50, v51
	v_mul_f32_e32 v51, 0xbfb8aa3b, v58
	v_exp_f32_e32 v51, v51
	s_nop 0
	v_add_f32_e32 v51, 1.0, v51
	v_rcp_f32_e32 v52, v51
	v_mul_f32_e32 v51, 0xbfb8aa3b, v59
	v_exp_f32_e32 v51, v51
	s_nop 0
	v_add_f32_e32 v51, 1.0, v51
	v_rcp_f32_e32 v53, v51
	s_nop 0
	v_pk_mul_f32 v[52:53], v[58:59], v[52:53]
	s_nop 0
	v_pk_mul_f32 v[52:53], v[66:67], v[52:53]
	s_nop 0
	v_cvt_pk_bf16_f32 v51, v52, v53
	global_store_dwordx4 v[64:65], v[48:51], off sc1
	s_nop 1
	v_pk_mul_f32 v[50:51], v[34:35], v[146:147] op_sel_hi:[1,0]
	v_pk_mul_f32 v[34:35], v[32:33], v[146:147] op_sel_hi:[1,0]
	v_mul_f32_e32 v32, 0xbfb8aa3b, v44
	v_mul_f32_e32 v33, 0xbfb8aa3b, v45
	v_exp_f32_e32 v32, v32
	v_exp_f32_e32 v33, v33
	v_add_u32_e32 v48, 0x90, v210
	v_mad_i64_i32 v[48:49], s[0:1], v48, s2, v[132:133]
	v_add_f32_e32 v32, 1.0, v32
	v_add_f32_e32 v33, 1.0, v33
	v_rcp_f32_e32 v32, v32
	v_rcp_f32_e32 v33, v33
	v_lshl_add_u64 v[48:49], v[48:49], 0, v[134:135]
	v_pk_mul_f32 v[32:33], v[44:45], v[32:33]
	s_nop 0
	v_pk_mul_f32 v[32:33], v[36:37], v[32:33]
	s_nop 0
	v_cvt_pk_bf16_f32 v32, v32, v33
	v_mul_f32_e32 v33, 0xbfb8aa3b, v46
	v_exp_f32_e32 v33, v33
	s_nop 0
	v_add_f32_e32 v33, 1.0, v33
	v_rcp_f32_e32 v36, v33
	v_mul_f32_e32 v33, 0xbfb8aa3b, v47
	v_exp_f32_e32 v33, v33
	s_nop 0
	v_add_f32_e32 v33, 1.0, v33
	v_rcp_f32_e32 v37, v33
	s_nop 0
	v_pk_mul_f32 v[36:37], v[46:47], v[36:37]
	s_nop 0
	v_pk_mul_f32 v[36:37], v[38:39], v[36:37]
	s_nop 0
	v_cvt_pk_bf16_f32 v33, v36, v37
	v_mul_f32_e32 v36, 0xbfb8aa3b, v40
	v_mul_f32_e32 v37, 0xbfb8aa3b, v41
	v_exp_f32_e32 v36, v36
	v_exp_f32_e32 v37, v37
	v_add_f32_e32 v36, 1.0, v36
	v_add_f32_e32 v37, 1.0, v37
	v_rcp_f32_e32 v36, v36
	v_rcp_f32_e32 v37, v37
	s_nop 0
	v_pk_mul_f32 v[36:37], v[40:41], v[36:37]
	s_nop 0
	v_pk_mul_f32 v[34:35], v[34:35], v[36:37]
	s_nop 0
	v_cvt_pk_bf16_f32 v34, v34, v35
	v_mul_f32_e32 v35, 0xbfb8aa3b, v42
	v_exp_f32_e32 v35, v35
	s_nop 0
	v_add_f32_e32 v35, 1.0, v35
	v_rcp_f32_e32 v36, v35
	v_mul_f32_e32 v35, 0xbfb8aa3b, v43
	v_exp_f32_e32 v35, v35
	s_nop 0
	v_add_f32_e32 v35, 1.0, v35
	v_rcp_f32_e32 v37, v35
	s_nop 0
	v_pk_mul_f32 v[36:37], v[42:43], v[36:37]
	s_nop 0
	v_pk_mul_f32 v[36:37], v[50:51], v[36:37]
	s_nop 0
	v_cvt_pk_bf16_f32 v35, v36, v37
	global_store_dwordx4 v[48:49], v[32:35], off sc1
	s_nop 1
	v_pk_mul_f32 v[34:35], v[18:19], v[136:137] op_sel_hi:[1,0]
	v_pk_mul_f32 v[18:19], v[16:17], v[136:137] op_sel_hi:[1,0]
	v_mul_f32_e32 v16, 0xbfb8aa3b, v28
	v_mul_f32_e32 v17, 0xbfb8aa3b, v29
	v_exp_f32_e32 v16, v16
	v_exp_f32_e32 v17, v17
	v_add_u32_e32 v32, 0xa0, v210
	v_mad_i64_i32 v[32:33], s[0:1], v32, s2, v[132:133]
	v_add_f32_e32 v16, 1.0, v16
	v_add_f32_e32 v17, 1.0, v17
	v_rcp_f32_e32 v16, v16
	v_rcp_f32_e32 v17, v17
	v_lshl_add_u64 v[32:33], v[32:33], 0, v[134:135]
	v_pk_mul_f32 v[16:17], v[28:29], v[16:17]
	s_nop 0
	v_pk_mul_f32 v[16:17], v[20:21], v[16:17]
	s_nop 0
	v_cvt_pk_bf16_f32 v16, v16, v17
	v_mul_f32_e32 v17, 0xbfb8aa3b, v30
	v_exp_f32_e32 v17, v17
	s_nop 0
	v_add_f32_e32 v17, 1.0, v17
	v_rcp_f32_e32 v20, v17
	v_mul_f32_e32 v17, 0xbfb8aa3b, v31
	v_exp_f32_e32 v17, v17
	s_nop 0
	v_add_f32_e32 v17, 1.0, v17
	v_rcp_f32_e32 v21, v17
	s_nop 0
	v_pk_mul_f32 v[20:21], v[30:31], v[20:21]
	s_nop 0
	v_pk_mul_f32 v[20:21], v[22:23], v[20:21]
	s_nop 0
	v_cvt_pk_bf16_f32 v17, v20, v21
	v_mul_f32_e32 v20, 0xbfb8aa3b, v24
	v_mul_f32_e32 v21, 0xbfb8aa3b, v25
	v_exp_f32_e32 v20, v20
	v_exp_f32_e32 v21, v21
	v_add_f32_e32 v20, 1.0, v20
	v_add_f32_e32 v21, 1.0, v21
	v_rcp_f32_e32 v20, v20
	v_rcp_f32_e32 v21, v21
	s_nop 0
	v_pk_mul_f32 v[20:21], v[24:25], v[20:21]
	s_nop 0
	v_pk_mul_f32 v[18:19], v[18:19], v[20:21]
	s_nop 0
	v_cvt_pk_bf16_f32 v18, v18, v19
	v_mul_f32_e32 v19, 0xbfb8aa3b, v26
	v_exp_f32_e32 v19, v19
	s_nop 0
	v_add_f32_e32 v19, 1.0, v19
	v_rcp_f32_e32 v20, v19
	v_mul_f32_e32 v19, 0xbfb8aa3b, v27
	v_exp_f32_e32 v19, v19
	s_nop 0
	v_add_f32_e32 v19, 1.0, v19
	v_rcp_f32_e32 v21, v19
	s_nop 0
	v_pk_mul_f32 v[20:21], v[26:27], v[20:21]
	s_nop 0
	v_pk_mul_f32 v[20:21], v[34:35], v[20:21]
	s_nop 0
	v_cvt_pk_bf16_f32 v19, v20, v21
	global_store_dwordx4 v[32:33], v[16:19], off sc1
	s_nop 1
	v_pk_mul_f32 v[18:19], v[2:3], v[130:131] op_sel_hi:[1,0]
	v_pk_mul_f32 v[2:3], v[0:1], v[130:131] op_sel_hi:[1,0]
	v_mul_f32_e32 v0, 0xbfb8aa3b, v12
	v_mul_f32_e32 v1, 0xbfb8aa3b, v13
	v_exp_f32_e32 v0, v0
	v_exp_f32_e32 v1, v1
	v_add_u32_e32 v16, 0xb0, v210
	v_mad_i64_i32 v[16:17], s[0:1], v16, s2, v[132:133]
	v_add_f32_e32 v0, 1.0, v0
	v_add_f32_e32 v1, 1.0, v1
	v_rcp_f32_e32 v0, v0
	v_rcp_f32_e32 v1, v1
	v_lshl_add_u64 v[16:17], v[16:17], 0, v[134:135]
	s_mov_b64 s[0:1], -1
	v_pk_mul_f32 v[0:1], v[12:13], v[0:1]
	s_nop 0
	v_pk_mul_f32 v[0:1], v[4:5], v[0:1]
	s_nop 0
	v_cvt_pk_bf16_f32 v0, v0, v1
	v_mul_f32_e32 v1, 0xbfb8aa3b, v14
	v_exp_f32_e32 v1, v1
	s_nop 0
	v_add_f32_e32 v1, 1.0, v1
	v_rcp_f32_e32 v4, v1
	v_mul_f32_e32 v1, 0xbfb8aa3b, v15
	v_exp_f32_e32 v1, v1
	s_nop 0
	v_add_f32_e32 v1, 1.0, v1
	v_rcp_f32_e32 v5, v1
	s_nop 0
	v_pk_mul_f32 v[4:5], v[14:15], v[4:5]
	s_nop 0
	v_pk_mul_f32 v[4:5], v[6:7], v[4:5]
	s_nop 0
	v_cvt_pk_bf16_f32 v1, v4, v5
	v_mul_f32_e32 v4, 0xbfb8aa3b, v8
	v_mul_f32_e32 v5, 0xbfb8aa3b, v9
	v_exp_f32_e32 v4, v4
	v_exp_f32_e32 v5, v5
	v_add_f32_e32 v4, 1.0, v4
	v_add_f32_e32 v5, 1.0, v5
	v_rcp_f32_e32 v4, v4
	v_rcp_f32_e32 v5, v5
	s_nop 0
	v_pk_mul_f32 v[4:5], v[8:9], v[4:5]
	s_nop 0
	v_pk_mul_f32 v[2:3], v[2:3], v[4:5]
	s_nop 0
	v_cvt_pk_bf16_f32 v2, v2, v3
	v_mul_f32_e32 v3, 0xbfb8aa3b, v10
	v_exp_f32_e32 v3, v3
	s_nop 0
	v_add_f32_e32 v3, 1.0, v3
	v_rcp_f32_e32 v4, v3
	v_mul_f32_e32 v3, 0xbfb8aa3b, v11
	v_exp_f32_e32 v3, v3
	s_nop 0
	v_add_f32_e32 v3, 1.0, v3
	v_rcp_f32_e32 v5, v3
	s_nop 0
	v_pk_mul_f32 v[4:5], v[10:11], v[4:5]
	s_nop 0
	v_pk_mul_f32 v[4:5], v[18:19], v[4:5]
	s_nop 0
	v_cvt_pk_bf16_f32 v3, v4, v5
	global_store_dwordx4 v[16:17], v[0:3], off sc1
	s_cbranch_vccnz .LBB0_413
	s_andn2_b64 vcc, exec, s[10:11]
	s_cbranch_vccnz .LBB0_412
	s_barrier
	s_branch .LBB0_412

; __device__ __forceinline__ unsigned pk_bf16(float lo, float hi) { f32x2e v = {lo, hi}; bf16x2e b = __builtin_convertvector(v, bf16x2e); return __builtin_bit_cast(unsigned, b); }
;     __device__ __forceinline__ void operator()(const f32x4 (&acc)[2][2][4][2], const Unit& u, int wr, int wc, int fr, int fq) const {
;         const int col0 = u.pn * BM + wc * 32 + 8 * fq;
;         bf16_t* base = H + (size_t)(u.pm * BM + wr * 64 + fr) * ldc + col0;
;         u32x4 r[2][4][2];
; #pragma unroll
;         for (int ai = 0; ai < 2; ++ai)
; #pragma unroll
;             for (int m = 0; m < 4; ++m)
; #pragma unroll
;                 for (int bj = 0; bj < 2; ++bj) r[ai][m][bj] = *(const u32x4*)(base + (size_t)(ai * HALF + m * 16) * ldc + bj * HALF);
; #pragma unroll
;         for (int ai = 0; ai < 2; ++ai)
; #pragma unroll
;             for (int m = 0; m < 4; ++m) { const int row = u.pm * BM + ai * HALF + wr * 64 + m * 16 + fr; bf16_t* rowp = base + (size_t)(ai * HALF + m * 16) * ldc;
;                 float qs = 0.f;
; #pragma unroll
;                 for (int bj = 0; bj < 2; ++bj) { const f32x4 a0 = acc[ai][bj][m][0], a1 = acc[ai][bj][m][1]; const u32x4 q = r[ai][m][bj]; u32x4 w;
;                     w.x = pk_bf16(__uint_as_float(q.x << 16) + a0.x, __uint_as_float(q.x & 0xffff0000u) + a0.y);
;                     w.y = pk_bf16(__uint_as_float(q.y << 16) + a0.z, __uint_as_float(q.y & 0xffff0000u) + a0.w);
;                     w.z = pk_bf16(__uint_as_float(q.z << 16) + a1.x, __uint_as_float(q.z & 0xffff0000u) + a1.y);
;                     w.w = pk_bf16(__uint_as_float(q.w << 16) + a1.z, __uint_as_float(q.w & 0xffff0000u) + a1.w);
;                     *(u32x4*)(rowp + bj * HALF) = w;
; #pragma unroll
;                     for (int e = 0; e < 4; ++e) { const float h0 = __uint_as_float(w[e] << 16), h1 = __uint_as_float(w[e] & 0xffff0000u); qs += h0 * h0 + h1 * h1; } }
;                 qs += __shfl_xor(qs, 16); qs += __shfl_xor(qs, 32);
;                 if (fq == 0) ss[(size_t)row * 32 + u.pn * 4 + wc] = qs; }
.LBB0_450:
	v_lshl_add_u32 v212, s7, 8, v231
	v_ashrrev_i32_e32 v213, 31, v212
	v_readlane_b32 s0, v254, 59
	v_lshl_or_b32 v98, s6, 8, v233
	v_lshlrev_b64 v[100:101], 12, v[212:213]
	v_readlane_b32 s1, v254, 60
	v_ashrrev_i32_e32 v99, 31, v98
	v_and_b32_e32 v229, 64, v220
	v_lshl_add_u64 v[100:101], s[0:1], 0, v[100:101]
	v_lshl_add_u64 v[214:215], v[98:99], 1, v[100:101]
	global_load_dwordx4 v[190:193], v[214:215], off
	global_load_dwordx4 v[186:189], v[214:215], off offset:256
	s_mov_b32 s0, 0x10000
	v_add_co_u32_e32 v98, vcc, s0, v214
	s_mov_b32 s0, 0x20000
	s_nop 0
	v_addc_co_u32_e32 v99, vcc, 0, v215, vcc
	global_load_dwordx4 v[182:185], v[98:99], off
	global_load_dwordx4 v[178:181], v[98:99], off offset:256
	v_add_co_u32_e32 v98, vcc, s0, v214
	s_mov_b32 s0, 0x30000
	s_nop 0
	v_addc_co_u32_e32 v99, vcc, 0, v215, vcc
	global_load_dwordx4 v[174:177], v[98:99], off
	global_load_dwordx4 v[170:173], v[98:99], off offset:256
	v_add_co_u32_e32 v98, vcc, s0, v214
	s_mov_b32 s0, 0x80000
	s_nop 0
	v_addc_co_u32_e32 v99, vcc, 0, v215, vcc
	global_load_dwordx4 v[166:169], v[98:99], off
	global_load_dwordx4 v[162:165], v[98:99], off offset:256
	v_add_co_u32_e32 v98, vcc, s0, v214
	s_mov_b32 s0, 0x90000
	s_nop 0
	v_addc_co_u32_e32 v99, vcc, 0, v215, vcc
	global_load_dwordx4 v[158:161], v[98:99], off
	global_load_dwordx4 v[150:153], v[98:99], off offset:256
	v_add_co_u32_e32 v98, vcc, s0, v214
	s_mov_b32 s0, 0xa0000
	s_nop 0
	v_addc_co_u32_e32 v99, vcc, 0, v215, vcc
	global_load_dwordx4 v[142:145], v[98:99], off
	global_load_dwordx4 v[138:141], v[98:99], off offset:256
	v_add_co_u32_e32 v98, vcc, s0, v214
	s_mov_b32 s0, 0xb0000
	s_nop 0
	v_addc_co_u32_e32 v99, vcc, 0, v215, vcc
	global_load_dwordx4 v[126:129], v[98:99], off
	global_load_dwordx4 v[118:121], v[98:99], off offset:256
	v_add_co_u32_e32 v98, vcc, s0, v214
	v_xor_b32_e32 v228, 16, v220
	s_nop 0
	v_addc_co_u32_e32 v99, vcc, 0, v215, vcc
	global_load_dwordx4 v[106:109], v[98:99], off
	s_nop 0
	global_load_dwordx4 v[98:101], v[98:99], off offset:256
	v_add_u32_e32 v229, 64, v229
	v_cmp_lt_i32_e32 vcc, v228, v229
	s_lshl_b32 s66, s6, 2
	s_ashr_i32 s67, s66, 31
	v_cndmask_b32_e32 v228, v220, v228, vcc
	v_lshlrev_b32_e32 v235, 2, v228
	v_xor_b32_e32 v228, 32, v220
	v_cmp_lt_i32_e32 vcc, v228, v229
	s_waitcnt vmcnt(0) lgkmcnt(0)
	v_and_b32_e32 v229, 0xffff0000, v190
	v_cndmask_b32_e32 v228, v220, v228, vcc
	v_lshlrev_b32_e32 v236, 2, v228
	v_lshlrev_b32_e32 v228, 16, v190
	v_lshlrev_b32_e32 v190, 16, v191
	v_and_b32_e32 v191, 0xffff0000, v191
	v_pk_add_f32 v[154:155], v[154:155], v[228:229]
	v_pk_add_f32 v[156:157], v[156:157], v[190:191]
	v_cvt_pk_bf16_f32 v154, v154, v155
	v_cvt_pk_bf16_f32 v155, v156, v157
	v_lshlrev_b32_e32 v156, 16, v192
	v_and_b32_e32 v157, 0xffff0000, v192
	v_pk_add_f32 v[146:147], v[146:147], v[156:157]
	s_nop 0
	v_cvt_pk_bf16_f32 v156, v146, v147
	v_lshlrev_b32_e32 v146, 16, v193
	v_and_b32_e32 v147, 0xffff0000, v193
	v_pk_add_f32 v[146:147], v[148:149], v[146:147]
	v_and_b32_e32 v148, 0xffff0000, v155
	v_cvt_pk_bf16_f32 v157, v146, v147
	v_and_b32_e32 v147, 0xffff0000, v154
	v_lshlrev_b32_e32 v146, 16, v154
	v_mul_f32_e32 v147, v147, v147
	v_fmac_f32_e32 v147, v146, v146
	v_lshlrev_b32_e32 v146, 16, v155
	v_mul_f32_e32 v148, v148, v148
	v_fmac_f32_e32 v148, v146, v146
	v_add_f32_e32 v146, v147, v148
	v_and_b32_e32 v148, 0xffff0000, v156
	v_lshlrev_b32_e32 v147, 16, v156
	v_mul_f32_e32 v148, v148, v148
	v_fmac_f32_e32 v148, v147, v147
	v_add_f32_e32 v146, v148, v146
	v_and_b32_e32 v148, 0xffff0000, v157
	v_lshlrev_b32_e32 v147, 16, v157
	v_mul_f32_e32 v148, v148, v148
	v_fmac_f32_e32 v148, v147, v147
	v_add_f32_e32 v148, v148, v146
	v_lshlrev_b32_e32 v146, 16, v186
	v_and_b32_e32 v147, 0xffff0000, v186
	v_pk_add_f32 v[134:135], v[134:135], v[146:147]
	v_lshlrev_b32_e32 v146, 16, v187
	v_and_b32_e32 v147, 0xffff0000, v187
	v_pk_add_f32 v[136:137], v[136:137], v[146:147]
	v_cvt_pk_bf16_f32 v134, v134, v135
	v_cvt_pk_bf16_f32 v135, v136, v137
	v_lshlrev_b32_e32 v136, 16, v188
	v_and_b32_e32 v137, 0xffff0000, v188
	v_pk_add_f32 v[130:131], v[130:131], v[136:137]
	global_store_dwordx4 v[214:215], v[154:157], off sc1
	v_cvt_pk_bf16_f32 v136, v130, v131
	v_lshlrev_b32_e32 v130, 16, v189
	v_and_b32_e32 v131, 0xffff0000, v189
	v_pk_add_f32 v[130:131], v[132:133], v[130:131]
	v_and_b32_e32 v132, 0xffff0000, v135
	v_cvt_pk_bf16_f32 v137, v130, v131
	v_and_b32_e32 v131, 0xffff0000, v134
	v_lshlrev_b32_e32 v130, 16, v134
	v_mul_f32_e32 v131, v131, v131
	v_fmac_f32_e32 v131, v130, v130
	v_add_f32_e32 v130, v131, v148
	v_lshlrev_b32_e32 v131, 16, v135
	v_mul_f32_e32 v132, v132, v132
	v_fmac_f32_e32 v132, v131, v131
	v_add_f32_e32 v130, v132, v130
	v_and_b32_e32 v132, 0xffff0000, v136
	v_lshlrev_b32_e32 v131, 16, v136
	v_mul_f32_e32 v132, v132, v132
	v_fmac_f32_e32 v132, v131, v131
	v_add_f32_e32 v130, v132, v130
	v_and_b32_e32 v132, 0xffff0000, v137
	v_lshlrev_b32_e32 v131, 16, v137
	v_mul_f32_e32 v132, v132, v132
	v_fmac_f32_e32 v132, v131, v131
	v_add_f32_e32 v130, v132, v130
	ds_bpermute_b32 v131, v235, v130
	global_store_dwordx4 v[214:215], v[134:137], off offset:256 sc1
	s_waitcnt lgkmcnt(0)
	v_add_f32_e32 v130, v130, v131
	ds_bpermute_b32 v131, v236, v130
	s_and_saveexec_b64 s[0:1], s[38:39]
	s_cbranch_execz .LBB0_452
	v_lshlrev_b64 v[132:133], 7, v[212:213]
	v_lshl_add_u64 v[132:133], s[44:45], 0, v[132:133]
	v_lshl_add_u64 v[132:133], s[66:67], 2, v[132:133]
	s_lshl_b32 s28, s47, 2
	v_lshl_add_u64 v[132:133], v[132:133], 0, s[28:29]
	s_waitcnt lgkmcnt(0)
	v_add_f32_e32 v130, v130, v131
	global_store_dword v[132:133], v130, off sc1
; __device__ __forceinline__ unsigned pk_bf16(float lo, float hi) { f32x2e v = {lo, hi}; bf16x2e b = __builtin_convertvector(v, bf16x2e); return __builtin_bit_cast(unsigned, b); }
;     __device__ __forceinline__ void operator()(const f32x4 (&acc)[2][2][4][2], const Unit& u, int wr, int wc, int fr, int fq) const {
;     ...
;             for (int m = 0; m < 4; ++m) { const int row = u.pm * BM + ai * HALF + wr * 64 + m * 16 + fr; bf16_t* rowp = base + (size_t)(ai * HALF + m * 16) * ldc;
;                 float qs = 0.f;
; #pragma unroll
;                 for (int bj = 0; bj < 2; ++bj) { const f32x4 a0 = acc[ai][bj][m][0], a1 = acc[ai][bj][m][1]; const u32x4 q = r[ai][m][bj]; u32x4 w;
;                     w.x = pk_bf16(__uint_as_float(q.x << 16) + a0.x, __uint_as_float(q.x & 0xffff0000u) + a0.y);
;                     w.y = pk_bf16(__uint_as_float(q.y << 16) + a0.z, __uint_as_float(q.y & 0xffff0000u) + a0.w);
;                     w.z = pk_bf16(__uint_as_float(q.z << 16) + a1.x, __uint_as_float(q.z & 0xffff0000u) + a1.y);
;                     w.w = pk_bf16(__uint_as_float(q.w << 16) + a1.z, __uint_as_float(q.w & 0xffff0000u) + a1.w);
;                     *(u32x4*)(rowp + bj * HALF) = w;
; #pragma unroll
;                     for (int e = 0; e < 4; ++e) { const float h0 = __uint_as_float(w[e] << 16), h1 = __uint_as_float(w[e] & 0xffff0000u); qs += h0 * h0 + h1 * h1; } }
;                 qs += __shfl_xor(qs, 16); qs += __shfl_xor(qs, 32);
;                 if (fq == 0) ss[(size_t)row * 32 + u.pn * 4 + wc] = qs; }
.LBB0_452:
	s_or_b64 exec, exec, s[0:1]
	v_lshlrev_b32_e32 v130, 16, v182
	s_waitcnt lgkmcnt(0)
	v_and_b32_e32 v131, 0xffff0000, v182
	v_pk_add_f32 v[122:123], v[122:123], v[130:131]
	v_lshlrev_b32_e32 v130, 16, v183
	v_and_b32_e32 v131, 0xffff0000, v183
	v_pk_add_f32 v[124:125], v[124:125], v[130:131]
	v_cvt_pk_bf16_f32 v122, v122, v123
	v_cvt_pk_bf16_f32 v123, v124, v125
	v_lshlrev_b32_e32 v124, 16, v184
	v_and_b32_e32 v125, 0xffff0000, v184
	v_pk_add_f32 v[114:115], v[114:115], v[124:125]
	s_mov_b64 s[0:1], 0x10000
	v_cvt_pk_bf16_f32 v124, v114, v115
	v_lshlrev_b32_e32 v114, 16, v185
	v_and_b32_e32 v115, 0xffff0000, v185
	v_pk_add_f32 v[114:115], v[116:117], v[114:115]
	v_and_b32_e32 v116, 0xffff0000, v123
	v_cvt_pk_bf16_f32 v125, v114, v115
	v_and_b32_e32 v115, 0xffff0000, v122
	v_lshlrev_b32_e32 v114, 16, v122
	v_mul_f32_e32 v115, v115, v115
	v_fmac_f32_e32 v115, v114, v114
	v_lshlrev_b32_e32 v114, 16, v123
	v_mul_f32_e32 v116, v116, v116
	v_fmac_f32_e32 v116, v114, v114
	v_add_f32_e32 v114, v115, v116
	v_and_b32_e32 v116, 0xffff0000, v124
	v_lshlrev_b32_e32 v115, 16, v124
	v_mul_f32_e32 v116, v116, v116
	v_fmac_f32_e32 v116, v115, v115
	v_add_f32_e32 v114, v116, v114
	v_and_b32_e32 v116, 0xffff0000, v125
	v_lshlrev_b32_e32 v115, 16, v125
	v_mul_f32_e32 v116, v116, v116
	v_fmac_f32_e32 v116, v115, v115
	v_add_f32_e32 v116, v116, v114
	v_lshlrev_b32_e32 v114, 16, v178
	v_and_b32_e32 v115, 0xffff0000, v178
	v_pk_add_f32 v[110:111], v[110:111], v[114:115]
	v_lshlrev_b32_e32 v114, 16, v179
	v_and_b32_e32 v115, 0xffff0000, v179
	v_pk_add_f32 v[112:113], v[112:113], v[114:115]
	v_cvt_pk_bf16_f32 v110, v110, v111
	v_cvt_pk_bf16_f32 v111, v112, v113
	v_lshlrev_b32_e32 v112, 16, v180
	v_and_b32_e32 v113, 0xffff0000, v180
	v_pk_add_f32 v[102:103], v[102:103], v[112:113]
	s_nop 0
	v_cvt_pk_bf16_f32 v112, v102, v103
	v_lshlrev_b32_e32 v102, 16, v181
	v_and_b32_e32 v103, 0xffff0000, v181
	v_pk_add_f32 v[102:103], v[104:105], v[102:103]
	v_and_b32_e32 v104, 0xffff0000, v111
	v_cvt_pk_bf16_f32 v113, v102, v103
	v_and_b32_e32 v103, 0xffff0000, v110
	v_lshlrev_b32_e32 v102, 16, v110
	v_mul_f32_e32 v103, v103, v103
	v_fmac_f32_e32 v103, v102, v102
	v_add_f32_e32 v102, v103, v116
	v_lshlrev_b32_e32 v103, 16, v111
	v_mul_f32_e32 v104, v104, v104
	v_fmac_f32_e32 v104, v103, v103
	v_add_f32_e32 v102, v104, v102
	v_and_b32_e32 v104, 0xffff0000, v112
	v_lshlrev_b32_e32 v103, 16, v112
	v_mul_f32_e32 v104, v104, v104
	v_fmac_f32_e32 v104, v103, v103
	v_add_f32_e32 v102, v104, v102
	v_and_b32_e32 v104, 0xffff0000, v113
	v_lshlrev_b32_e32 v103, 16, v113
	v_mul_f32_e32 v104, v104, v104
	v_fmac_f32_e32 v104, v103, v103
	v_add_f32_e32 v102, v104, v102
	ds_bpermute_b32 v103, v235, v102
	v_lshl_add_u64 v[104:105], v[214:215], 0, s[0:1]
	s_mov_b64 s[0:1], 0x10100
	v_lshl_add_u64 v[114:115], v[214:215], 0, s[0:1]
	global_store_dwordx4 v[104:105], v[122:125], off sc1
	global_store_dwordx4 v[114:115], v[110:113], off sc1
	s_waitcnt lgkmcnt(0)
	v_add_f32_e32 v102, v102, v103
	ds_bpermute_b32 v103, v236, v102
	s_and_saveexec_b64 s[0:1], s[38:39]
	s_cbranch_execz .LBB0_454
	v_or_b32_e32 v104, 16, v212
	v_ashrrev_i32_e32 v105, 31, v104
	s_waitcnt lgkmcnt(0)
	v_add_f32_e32 v110, v102, v103
	v_lshlrev_b64 v[102:103], 7, v[104:105]
	v_lshl_add_u64 v[102:103], s[44:45], 0, v[102:103]
	v_lshl_add_u64 v[102:103], s[66:67], 2, v[102:103]
	s_lshl_b32 s28, s47, 2
	v_lshl_add_u64 v[102:103], v[102:103], 0, s[28:29]
	global_store_dword v[102:103], v110, off sc1
.LBB0_454:
	s_or_b64 exec, exec, s[0:1]
	v_lshlrev_b32_e32 v102, 16, v174
	s_waitcnt lgkmcnt(0)
	v_and_b32_e32 v103, 0xffff0000, v174
	v_pk_add_f32 v[92:93], v[92:93], v[102:103]
	v_lshlrev_b32_e32 v102, 16, v175
	v_and_b32_e32 v103, 0xffff0000, v175
	v_pk_add_f32 v[94:95], v[94:95], v[102:103]
	v_cvt_pk_bf16_f32 v92, v92, v93
	v_cvt_pk_bf16_f32 v93, v94, v95
	v_lshlrev_b32_e32 v94, 16, v176
	v_and_b32_e32 v95, 0xffff0000, v176
	v_pk_add_f32 v[88:89], v[88:89], v[94:95]
	s_mov_b64 s[0:1], 0x20000
	v_cvt_pk_bf16_f32 v94, v88, v89
	v_lshlrev_b32_e32 v88, 16, v177
	v_and_b32_e32 v89, 0xffff0000, v177
	v_pk_add_f32 v[88:89], v[90:91], v[88:89]
	v_and_b32_e32 v90, 0xffff0000, v93
	v_cvt_pk_bf16_f32 v95, v88, v89
	v_and_b32_e32 v89, 0xffff0000, v92
	v_lshlrev_b32_e32 v88, 16, v92
	v_mul_f32_e32 v89, v89, v89
	v_fmac_f32_e32 v89, v88, v88
	v_lshlrev_b32_e32 v88, 16, v93
	v_mul_f32_e32 v90, v90, v90
	v_fmac_f32_e32 v90, v88, v88
	v_add_f32_e32 v88, v89, v90
	v_and_b32_e32 v90, 0xffff0000, v94
	v_lshlrev_b32_e32 v89, 16, v94
	v_mul_f32_e32 v90, v90, v90
	v_fmac_f32_e32 v90, v89, v89
	v_add_f32_e32 v88, v90, v88
	v_and_b32_e32 v90, 0xffff0000, v95
	v_lshlrev_b32_e32 v89, 16, v95
	v_mul_f32_e32 v90, v90, v90
	v_fmac_f32_e32 v90, v89, v89
	v_add_f32_e32 v90, v90, v88
	v_lshlrev_b32_e32 v88, 16, v170
	v_and_b32_e32 v89, 0xffff0000, v170
	v_pk_add_f32 v[84:85], v[84:85], v[88:89]
	v_lshlrev_b32_e32 v88, 16, v171
	v_and_b32_e32 v89, 0xffff0000, v171
	v_pk_add_f32 v[86:87], v[86:87], v[88:89]
	v_cvt_pk_bf16_f32 v84, v84, v85
	v_cvt_pk_bf16_f32 v85, v86, v87
	v_lshlrev_b32_e32 v86, 16, v172
	v_and_b32_e32 v87, 0xffff0000, v172
	v_pk_add_f32 v[80:81], v[80:81], v[86:87]
	s_nop 0
	v_cvt_pk_bf16_f32 v86, v80, v81
	v_lshlrev_b32_e32 v80, 16, v173
	v_and_b32_e32 v81, 0xffff0000, v173
	v_pk_add_f32 v[80:81], v[82:83], v[80:81]
	v_and_b32_e32 v82, 0xffff0000, v85
	v_cvt_pk_bf16_f32 v87, v80, v81
	v_and_b32_e32 v81, 0xffff0000, v84
	v_lshlrev_b32_e32 v80, 16, v84
	v_mul_f32_e32 v81, v81, v81
	v_fmac_f32_e32 v81, v80, v80
	v_add_f32_e32 v80, v81, v90
	v_lshlrev_b32_e32 v81, 16, v85
	v_mul_f32_e32 v82, v82, v82
	v_fmac_f32_e32 v82, v81, v81
	v_add_f32_e32 v80, v82, v80
	v_and_b32_e32 v82, 0xffff0000, v86
	v_lshlrev_b32_e32 v81, 16, v86
	v_mul_f32_e32 v82, v82, v82
	v_fmac_f32_e32 v82, v81, v81
	v_add_f32_e32 v80, v82, v80
	v_and_b32_e32 v82, 0xffff0000, v87
	v_lshlrev_b32_e32 v81, 16, v87
	v_mul_f32_e32 v82, v82, v82
	v_fmac_f32_e32 v82, v81, v81
	v_add_f32_e32 v80, v82, v80
	ds_bpermute_b32 v81, v235, v80
	v_lshl_add_u64 v[82:83], v[214:215], 0, s[0:1]
	s_mov_b64 s[0:1], 0x20100
	v_lshl_add_u64 v[88:89], v[214:215], 0, s[0:1]
	global_store_dwordx4 v[82:83], v[92:95], off sc1
	global_store_dwordx4 v[88:89], v[84:87], off sc1
	s_waitcnt lgkmcnt(0)
	v_add_f32_e32 v80, v80, v81
	ds_bpermute_b32 v81, v236, v80
	s_and_saveexec_b64 s[0:1], s[38:39]
	s_cbranch_execz .LBB0_456
	v_or_b32_e32 v82, 32, v212
	v_ashrrev_i32_e32 v83, 31, v82
	s_waitcnt lgkmcnt(0)
	v_add_f32_e32 v84, v80, v81
	v_lshlrev_b64 v[80:81], 7, v[82:83]
	v_lshl_add_u64 v[80:81], s[44:45], 0, v[80:81]
	v_lshl_add_u64 v[80:81], s[66:67], 2, v[80:81]
	s_lshl_b32 s28, s47, 2
	v_lshl_add_u64 v[80:81], v[80:81], 0, s[28:29]
	global_store_dword v[80:81], v84, off sc1
; __device__ __forceinline__ unsigned pk_bf16(float lo, float hi) { f32x2e v = {lo, hi}; bf16x2e b = __builtin_convertvector(v, bf16x2e); return __builtin_bit_cast(unsigned, b); }
;     __device__ __forceinline__ void operator()(const f32x4 (&acc)[2][2][4][2], const Unit& u, int wr, int wc, int fr, int fq) const {
;     ...
;             for (int m = 0; m < 4; ++m) { const int row = u.pm * BM + ai * HALF + wr * 64 + m * 16 + fr; bf16_t* rowp = base + (size_t)(ai * HALF + m * 16) * ldc;
;                 float qs = 0.f;
; #pragma unroll
;                 for (int bj = 0; bj < 2; ++bj) { const f32x4 a0 = acc[ai][bj][m][0], a1 = acc[ai][bj][m][1]; const u32x4 q = r[ai][m][bj]; u32x4 w;
;                     w.x = pk_bf16(__uint_as_float(q.x << 16) + a0.x, __uint_as_float(q.x & 0xffff0000u) + a0.y);
;                     w.y = pk_bf16(__uint_as_float(q.y << 16) + a0.z, __uint_as_float(q.y & 0xffff0000u) + a0.w);
;                     w.z = pk_bf16(__uint_as_float(q.z << 16) + a1.x, __uint_as_float(q.z & 0xffff0000u) + a1.y);
;                     w.w = pk_bf16(__uint_as_float(q.w << 16) + a1.z, __uint_as_float(q.w & 0xffff0000u) + a1.w);
;                     *(u32x4*)(rowp + bj * HALF) = w;
; #pragma unroll
;                     for (int e = 0; e < 4; ++e) { const float h0 = __uint_as_float(w[e] << 16), h1 = __uint_as_float(w[e] & 0xffff0000u); qs += h0 * h0 + h1 * h1; } }
;                 qs += __shfl_xor(qs, 16); qs += __shfl_xor(qs, 32);
;                 if (fq == 0) ss[(size_t)row * 32 + u.pn * 4 + wc] = qs; }
.LBB0_456:
	s_or_b64 exec, exec, s[0:1]
	v_lshlrev_b32_e32 v80, 16, v166
	s_waitcnt lgkmcnt(0)
	v_and_b32_e32 v81, 0xffff0000, v166
	v_pk_add_f32 v[76:77], v[76:77], v[80:81]
	v_lshlrev_b32_e32 v80, 16, v167
	v_and_b32_e32 v81, 0xffff0000, v167
	v_pk_add_f32 v[78:79], v[78:79], v[80:81]
	v_cvt_pk_bf16_f32 v76, v76, v77
	v_cvt_pk_bf16_f32 v77, v78, v79
	v_lshlrev_b32_e32 v78, 16, v168
	v_and_b32_e32 v79, 0xffff0000, v168
	v_pk_add_f32 v[72:73], v[72:73], v[78:79]
	s_mov_b64 s[0:1], 0x30000
	v_cvt_pk_bf16_f32 v78, v72, v73
	v_lshlrev_b32_e32 v72, 16, v169
	v_and_b32_e32 v73, 0xffff0000, v169
	v_pk_add_f32 v[72:73], v[74:75], v[72:73]
	v_and_b32_e32 v74, 0xffff0000, v77
	v_cvt_pk_bf16_f32 v79, v72, v73
	v_and_b32_e32 v73, 0xffff0000, v76
	v_lshlrev_b32_e32 v72, 16, v76
	v_mul_f32_e32 v73, v73, v73
	v_fmac_f32_e32 v73, v72, v72
	v_lshlrev_b32_e32 v72, 16, v77
	v_mul_f32_e32 v74, v74, v74
	v_fmac_f32_e32 v74, v72, v72
	v_add_f32_e32 v72, v73, v74
	v_and_b32_e32 v74, 0xffff0000, v78
	v_lshlrev_b32_e32 v73, 16, v78
	v_mul_f32_e32 v74, v74, v74
	v_fmac_f32_e32 v74, v73, v73
	v_add_f32_e32 v72, v74, v72
	v_and_b32_e32 v74, 0xffff0000, v79
	v_lshlrev_b32_e32 v73, 16, v79
	v_mul_f32_e32 v74, v74, v74
	v_fmac_f32_e32 v74, v73, v73
	v_add_f32_e32 v74, v74, v72
	v_lshlrev_b32_e32 v72, 16, v162
	v_and_b32_e32 v73, 0xffff0000, v162
	v_pk_add_f32 v[68:69], v[68:69], v[72:73]
	v_lshlrev_b32_e32 v72, 16, v163
	v_and_b32_e32 v73, 0xffff0000, v163
	v_pk_add_f32 v[70:71], v[70:71], v[72:73]
	v_cvt_pk_bf16_f32 v68, v68, v69
	v_cvt_pk_bf16_f32 v69, v70, v71
	v_lshlrev_b32_e32 v70, 16, v164
	v_and_b32_e32 v71, 0xffff0000, v164
	v_pk_add_f32 v[64:65], v[64:65], v[70:71]
	s_nop 0
	v_cvt_pk_bf16_f32 v70, v64, v65
	v_lshlrev_b32_e32 v64, 16, v165
	v_and_b32_e32 v65, 0xffff0000, v165
	v_pk_add_f32 v[64:65], v[66:67], v[64:65]
	v_and_b32_e32 v66, 0xffff0000, v69
	v_cvt_pk_bf16_f32 v71, v64, v65
	v_and_b32_e32 v65, 0xffff0000, v68
	v_lshlrev_b32_e32 v64, 16, v68
	v_mul_f32_e32 v65, v65, v65
	v_fmac_f32_e32 v65, v64, v64
	v_add_f32_e32 v64, v65, v74
	v_lshlrev_b32_e32 v65, 16, v69
	v_mul_f32_e32 v66, v66, v66
	v_fmac_f32_e32 v66, v65, v65
	v_add_f32_e32 v64, v66, v64
	v_and_b32_e32 v66, 0xffff0000, v70
	v_lshlrev_b32_e32 v65, 16, v70
	v_mul_f32_e32 v66, v66, v66
	v_fmac_f32_e32 v66, v65, v65
	v_add_f32_e32 v64, v66, v64
	v_and_b32_e32 v66, 0xffff0000, v71
	v_lshlrev_b32_e32 v65, 16, v71
	v_mul_f32_e32 v66, v66, v66
	v_fmac_f32_e32 v66, v65, v65
	v_add_f32_e32 v64, v66, v64
	ds_bpermute_b32 v65, v235, v64
	v_lshl_add_u64 v[66:67], v[214:215], 0, s[0:1]
	s_mov_b64 s[0:1], 0x30100
	v_lshl_add_u64 v[72:73], v[214:215], 0, s[0:1]
	global_store_dwordx4 v[66:67], v[76:79], off sc1
	global_store_dwordx4 v[72:73], v[68:71], off sc1
	s_waitcnt lgkmcnt(0)
	v_add_f32_e32 v64, v64, v65
	ds_bpermute_b32 v65, v236, v64
	s_and_saveexec_b64 s[0:1], s[38:39]
	s_cbranch_execz .LBB0_458
	v_or_b32_e32 v66, 48, v212
	v_ashrrev_i32_e32 v67, 31, v66
	s_waitcnt lgkmcnt(0)
	v_add_f32_e32 v68, v64, v65
	v_lshlrev_b64 v[64:65], 7, v[66:67]
	v_lshl_add_u64 v[64:65], s[44:45], 0, v[64:65]
	v_lshl_add_u64 v[64:65], s[66:67], 2, v[64:65]
	s_lshl_b32 s28, s47, 2
	v_lshl_add_u64 v[64:65], v[64:65], 0, s[28:29]
	global_store_dword v[64:65], v68, off sc1
.LBB0_458:
	s_or_b64 exec, exec, s[0:1]
	v_lshlrev_b32_e32 v64, 16, v158
	s_waitcnt lgkmcnt(0)
	v_and_b32_e32 v65, 0xffff0000, v158
	v_pk_add_f32 v[60:61], v[60:61], v[64:65]
	v_lshlrev_b32_e32 v64, 16, v159
	v_and_b32_e32 v65, 0xffff0000, v159
	v_pk_add_f32 v[62:63], v[62:63], v[64:65]
	v_cvt_pk_bf16_f32 v60, v60, v61
	v_cvt_pk_bf16_f32 v61, v62, v63
	v_lshlrev_b32_e32 v62, 16, v160
	v_and_b32_e32 v63, 0xffff0000, v160
	v_pk_add_f32 v[56:57], v[56:57], v[62:63]
	s_mov_b64 s[0:1], 0x80000
	v_cvt_pk_bf16_f32 v62, v56, v57
	v_lshlrev_b32_e32 v56, 16, v161
	v_and_b32_e32 v57, 0xffff0000, v161
	v_pk_add_f32 v[56:57], v[58:59], v[56:57]
	v_and_b32_e32 v58, 0xffff0000, v61
	v_cvt_pk_bf16_f32 v63, v56, v57
	v_and_b32_e32 v57, 0xffff0000, v60
	v_lshlrev_b32_e32 v56, 16, v60
	v_mul_f32_e32 v57, v57, v57
	v_fmac_f32_e32 v57, v56, v56
	v_lshlrev_b32_e32 v56, 16, v61
	v_mul_f32_e32 v58, v58, v58
	v_fmac_f32_e32 v58, v56, v56
	v_add_f32_e32 v56, v57, v58
	v_and_b32_e32 v58, 0xffff0000, v62
	v_lshlrev_b32_e32 v57, 16, v62
	v_mul_f32_e32 v58, v58, v58
	v_fmac_f32_e32 v58, v57, v57
	v_add_f32_e32 v56, v58, v56
	v_and_b32_e32 v58, 0xffff0000, v63
	v_lshlrev_b32_e32 v57, 16, v63
	v_mul_f32_e32 v58, v58, v58
	v_fmac_f32_e32 v58, v57, v57
	v_add_f32_e32 v58, v58, v56
	v_lshlrev_b32_e32 v56, 16, v150
	v_and_b32_e32 v57, 0xffff0000, v150
	v_pk_add_f32 v[52:53], v[52:53], v[56:57]
	v_lshlrev_b32_e32 v56, 16, v151
	v_and_b32_e32 v57, 0xffff0000, v151
	v_pk_add_f32 v[54:55], v[54:55], v[56:57]
	v_cvt_pk_bf16_f32 v52, v52, v53
	v_cvt_pk_bf16_f32 v53, v54, v55
	v_lshlrev_b32_e32 v54, 16, v152
	v_and_b32_e32 v55, 0xffff0000, v152
	v_pk_add_f32 v[48:49], v[48:49], v[54:55]
	s_nop 0
	v_cvt_pk_bf16_f32 v54, v48, v49
	v_lshlrev_b32_e32 v48, 16, v153
	v_and_b32_e32 v49, 0xffff0000, v153
	v_pk_add_f32 v[48:49], v[50:51], v[48:49]
	v_and_b32_e32 v50, 0xffff0000, v53
	v_cvt_pk_bf16_f32 v55, v48, v49
	v_and_b32_e32 v49, 0xffff0000, v52
	v_lshlrev_b32_e32 v48, 16, v52
	v_mul_f32_e32 v49, v49, v49
	v_fmac_f32_e32 v49, v48, v48
	v_add_f32_e32 v48, v49, v58
	v_lshlrev_b32_e32 v49, 16, v53
	v_mul_f32_e32 v50, v50, v50
	v_fmac_f32_e32 v50, v49, v49
	v_add_f32_e32 v48, v50, v48
	v_and_b32_e32 v50, 0xffff0000, v54
	v_lshlrev_b32_e32 v49, 16, v54
	v_mul_f32_e32 v50, v50, v50
	v_fmac_f32_e32 v50, v49, v49
	v_add_f32_e32 v48, v50, v48
	v_and_b32_e32 v50, 0xffff0000, v55
	v_lshlrev_b32_e32 v49, 16, v55
	v_mul_f32_e32 v50, v50, v50
	v_fmac_f32_e32 v50, v49, v49
	v_add_f32_e32 v48, v50, v48
	ds_bpermute_b32 v49, v235, v48
	v_lshl_add_u64 v[50:51], v[214:215], 0, s[0:1]
	s_mov_b64 s[0:1], 0x80100
	v_lshl_add_u64 v[56:57], v[214:215], 0, s[0:1]
	global_store_dwordx4 v[50:51], v[60:63], off sc1
	global_store_dwordx4 v[56:57], v[52:55], off sc1
	s_waitcnt lgkmcnt(0)
	v_add_f32_e32 v48, v48, v49
	ds_bpermute_b32 v49, v236, v48
	s_and_saveexec_b64 s[0:1], s[38:39]
	s_cbranch_execz .LBB0_460
	v_add_u32_e32 v50, 0x80, v212
	v_ashrrev_i32_e32 v51, 31, v50
	s_waitcnt lgkmcnt(0)
	v_add_f32_e32 v52, v48, v49
	v_lshlrev_b64 v[48:49], 7, v[50:51]
	v_lshl_add_u64 v[48:49], s[44:45], 0, v[48:49]
	v_lshl_add_u64 v[48:49], s[66:67], 2, v[48:49]
	s_lshl_b32 s28, s47, 2
	v_lshl_add_u64 v[48:49], v[48:49], 0, s[28:29]
	global_store_dword v[48:49], v52, off sc1
; __device__ __forceinline__ unsigned pk_bf16(float lo, float hi) { f32x2e v = {lo, hi}; bf16x2e b = __builtin_convertvector(v, bf16x2e); return __builtin_bit_cast(unsigned, b); }
;     __device__ __forceinline__ void operator()(const f32x4 (&acc)[2][2][4][2], const Unit& u, int wr, int wc, int fr, int fq) const {
;     ...
;             for (int m = 0; m < 4; ++m) { const int row = u.pm * BM + ai * HALF + wr * 64 + m * 16 + fr; bf16_t* rowp = base + (size_t)(ai * HALF + m * 16) * ldc;
;                 float qs = 0.f;
; #pragma unroll
;                 for (int bj = 0; bj < 2; ++bj) { const f32x4 a0 = acc[ai][bj][m][0], a1 = acc[ai][bj][m][1]; const u32x4 q = r[ai][m][bj]; u32x4 w;
;                     w.x = pk_bf16(__uint_as_float(q.x << 16) + a0.x, __uint_as_float(q.x & 0xffff0000u) + a0.y);
;                     w.y = pk_bf16(__uint_as_float(q.y << 16) + a0.z, __uint_as_float(q.y & 0xffff0000u) + a0.w);
;                     w.z = pk_bf16(__uint_as_float(q.z << 16) + a1.x, __uint_as_float(q.z & 0xffff0000u) + a1.y);
;                     w.w = pk_bf16(__uint_as_float(q.w << 16) + a1.z, __uint_as_float(q.w & 0xffff0000u) + a1.w);
;                     *(u32x4*)(rowp + bj * HALF) = w;
; #pragma unroll
;                     for (int e = 0; e < 4; ++e) { const float h0 = __uint_as_float(w[e] << 16), h1 = __uint_as_float(w[e] & 0xffff0000u); qs += h0 * h0 + h1 * h1; } }
;                 qs += __shfl_xor(qs, 16); qs += __shfl_xor(qs, 32);
;                 if (fq == 0) ss[(size_t)row * 32 + u.pn * 4 + wc] = qs; }
.LBB0_460:
	s_or_b64 exec, exec, s[0:1]
	v_lshlrev_b32_e32 v48, 16, v142
	s_waitcnt lgkmcnt(0)
	v_and_b32_e32 v49, 0xffff0000, v142
	v_pk_add_f32 v[44:45], v[44:45], v[48:49]
	v_lshlrev_b32_e32 v48, 16, v143
	v_and_b32_e32 v49, 0xffff0000, v143
	v_pk_add_f32 v[46:47], v[46:47], v[48:49]
	v_cvt_pk_bf16_f32 v44, v44, v45
	v_cvt_pk_bf16_f32 v45, v46, v47
	v_lshlrev_b32_e32 v46, 16, v144
	v_and_b32_e32 v47, 0xffff0000, v144
	v_pk_add_f32 v[40:41], v[40:41], v[46:47]
	s_mov_b64 s[0:1], 0x90000
	v_cvt_pk_bf16_f32 v46, v40, v41
	v_lshlrev_b32_e32 v40, 16, v145
	v_and_b32_e32 v41, 0xffff0000, v145
	v_pk_add_f32 v[40:41], v[42:43], v[40:41]
	v_and_b32_e32 v42, 0xffff0000, v45
	v_cvt_pk_bf16_f32 v47, v40, v41
	v_and_b32_e32 v41, 0xffff0000, v44
	v_lshlrev_b32_e32 v40, 16, v44
	v_mul_f32_e32 v41, v41, v41
	v_fmac_f32_e32 v41, v40, v40
	v_lshlrev_b32_e32 v40, 16, v45
	v_mul_f32_e32 v42, v42, v42
	v_fmac_f32_e32 v42, v40, v40
	v_add_f32_e32 v40, v41, v42
	v_and_b32_e32 v42, 0xffff0000, v46
	v_lshlrev_b32_e32 v41, 16, v46
	v_mul_f32_e32 v42, v42, v42
	v_fmac_f32_e32 v42, v41, v41
	v_add_f32_e32 v40, v42, v40
	v_and_b32_e32 v42, 0xffff0000, v47
	v_lshlrev_b32_e32 v41, 16, v47
	v_mul_f32_e32 v42, v42, v42
	v_fmac_f32_e32 v42, v41, v41
	v_add_f32_e32 v42, v42, v40
	v_lshlrev_b32_e32 v40, 16, v138
	v_and_b32_e32 v41, 0xffff0000, v138
	v_pk_add_f32 v[36:37], v[36:37], v[40:41]
	v_lshlrev_b32_e32 v40, 16, v139
	v_and_b32_e32 v41, 0xffff0000, v139
	v_pk_add_f32 v[38:39], v[38:39], v[40:41]
	v_cvt_pk_bf16_f32 v36, v36, v37
	v_cvt_pk_bf16_f32 v37, v38, v39
	v_lshlrev_b32_e32 v38, 16, v140
	v_and_b32_e32 v39, 0xffff0000, v140
	v_pk_add_f32 v[32:33], v[32:33], v[38:39]
	s_nop 0
	v_cvt_pk_bf16_f32 v38, v32, v33
	v_lshlrev_b32_e32 v32, 16, v141
	v_and_b32_e32 v33, 0xffff0000, v141
	v_pk_add_f32 v[32:33], v[34:35], v[32:33]
	v_and_b32_e32 v34, 0xffff0000, v37
	v_cvt_pk_bf16_f32 v39, v32, v33
	v_and_b32_e32 v33, 0xffff0000, v36
	v_lshlrev_b32_e32 v32, 16, v36
	v_mul_f32_e32 v33, v33, v33
	v_fmac_f32_e32 v33, v32, v32
	v_add_f32_e32 v32, v33, v42
	v_lshlrev_b32_e32 v33, 16, v37
	v_mul_f32_e32 v34, v34, v34
	v_fmac_f32_e32 v34, v33, v33
	v_add_f32_e32 v32, v34, v32
	v_and_b32_e32 v34, 0xffff0000, v38
	v_lshlrev_b32_e32 v33, 16, v38
	v_mul_f32_e32 v34, v34, v34
	v_fmac_f32_e32 v34, v33, v33
	v_add_f32_e32 v32, v34, v32
	v_and_b32_e32 v34, 0xffff0000, v39
	v_lshlrev_b32_e32 v33, 16, v39
	v_mul_f32_e32 v34, v34, v34
	v_fmac_f32_e32 v34, v33, v33
	v_add_f32_e32 v32, v34, v32
	ds_bpermute_b32 v33, v235, v32
	v_lshl_add_u64 v[34:35], v[214:215], 0, s[0:1]
	s_mov_b64 s[0:1], 0x90100
	v_lshl_add_u64 v[40:41], v[214:215], 0, s[0:1]
	global_store_dwordx4 v[34:35], v[44:47], off sc1
	global_store_dwordx4 v[40:41], v[36:39], off sc1
	s_waitcnt lgkmcnt(0)
	v_add_f32_e32 v32, v32, v33
	ds_bpermute_b32 v33, v236, v32
	s_and_saveexec_b64 s[0:1], s[38:39]
	s_cbranch_execz .LBB0_462
	v_add_u32_e32 v34, 0x90, v212
	v_ashrrev_i32_e32 v35, 31, v34
	s_waitcnt lgkmcnt(0)
	v_add_f32_e32 v36, v32, v33
	v_lshlrev_b64 v[32:33], 7, v[34:35]
	v_lshl_add_u64 v[32:33], s[44:45], 0, v[32:33]
	v_lshl_add_u64 v[32:33], s[66:67], 2, v[32:33]
	s_lshl_b32 s28, s47, 2
	v_lshl_add_u64 v[32:33], v[32:33], 0, s[28:29]
	global_store_dword v[32:33], v36, off sc1
; __device__ __forceinline__ unsigned pk_bf16(float lo, float hi) { f32x2e v = {lo, hi}; bf16x2e b = __builtin_convertvector(v, bf16x2e); return __builtin_bit_cast(unsigned, b); }
;     __device__ __forceinline__ void operator()(const f32x4 (&acc)[2][2][4][2], const Unit& u, int wr, int wc, int fr, int fq) const {
;     ...
;             for (int m = 0; m < 4; ++m) { const int row = u.pm * BM + ai * HALF + wr * 64 + m * 16 + fr; bf16_t* rowp = base + (size_t)(ai * HALF + m * 16) * ldc;
;                 float qs = 0.f;
; #pragma unroll
;                 for (int bj = 0; bj < 2; ++bj) { const f32x4 a0 = acc[ai][bj][m][0], a1 = acc[ai][bj][m][1]; const u32x4 q = r[ai][m][bj]; u32x4 w;
;                     w.x = pk_bf16(__uint_as_float(q.x << 16) + a0.x, __uint_as_float(q.x & 0xffff0000u) + a0.y);
;                     w.y = pk_bf16(__uint_as_float(q.y << 16) + a0.z, __uint_as_float(q.y & 0xffff0000u) + a0.w);
;                     w.z = pk_bf16(__uint_as_float(q.z << 16) + a1.x, __uint_as_float(q.z & 0xffff0000u) + a1.y);
;                     w.w = pk_bf16(__uint_as_float(q.w << 16) + a1.z, __uint_as_float(q.w & 0xffff0000u) + a1.w);
;                     *(u32x4*)(rowp + bj * HALF) = w;
; #pragma unroll
;                     for (int e = 0; e < 4; ++e) { const float h0 = __uint_as_float(w[e] << 16), h1 = __uint_as_float(w[e] & 0xffff0000u); qs += h0 * h0 + h1 * h1; } }
;                 qs += __shfl_xor(qs, 16); qs += __shfl_xor(qs, 32);
;                 if (fq == 0) ss[(size_t)row * 32 + u.pn * 4 + wc] = qs; }
.LBB0_462:
	s_or_b64 exec, exec, s[0:1]
	v_lshlrev_b32_e32 v32, 16, v126
	s_waitcnt lgkmcnt(0)
	v_and_b32_e32 v33, 0xffff0000, v126
	v_pk_add_f32 v[28:29], v[28:29], v[32:33]
	v_lshlrev_b32_e32 v32, 16, v127
	v_and_b32_e32 v33, 0xffff0000, v127
	v_pk_add_f32 v[30:31], v[30:31], v[32:33]
	v_cvt_pk_bf16_f32 v28, v28, v29
	v_cvt_pk_bf16_f32 v29, v30, v31
	v_lshlrev_b32_e32 v30, 16, v128
	v_and_b32_e32 v31, 0xffff0000, v128
	v_pk_add_f32 v[24:25], v[24:25], v[30:31]
	s_mov_b64 s[0:1], 0xa0000
	v_cvt_pk_bf16_f32 v30, v24, v25
	v_lshlrev_b32_e32 v24, 16, v129
	v_and_b32_e32 v25, 0xffff0000, v129
	v_pk_add_f32 v[24:25], v[26:27], v[24:25]
	v_and_b32_e32 v26, 0xffff0000, v29
	v_cvt_pk_bf16_f32 v31, v24, v25
	v_and_b32_e32 v25, 0xffff0000, v28
	v_lshlrev_b32_e32 v24, 16, v28
	v_mul_f32_e32 v25, v25, v25
	v_fmac_f32_e32 v25, v24, v24
	v_lshlrev_b32_e32 v24, 16, v29
	v_mul_f32_e32 v26, v26, v26
	v_fmac_f32_e32 v26, v24, v24
	v_add_f32_e32 v24, v25, v26
	v_and_b32_e32 v26, 0xffff0000, v30
	v_lshlrev_b32_e32 v25, 16, v30
	v_mul_f32_e32 v26, v26, v26
	v_fmac_f32_e32 v26, v25, v25
	v_add_f32_e32 v24, v26, v24
	v_and_b32_e32 v26, 0xffff0000, v31
	v_lshlrev_b32_e32 v25, 16, v31
	v_mul_f32_e32 v26, v26, v26
	v_fmac_f32_e32 v26, v25, v25
	v_add_f32_e32 v26, v26, v24
	v_lshlrev_b32_e32 v24, 16, v118
	v_and_b32_e32 v25, 0xffff0000, v118
	v_pk_add_f32 v[20:21], v[20:21], v[24:25]
	v_lshlrev_b32_e32 v24, 16, v119
	v_and_b32_e32 v25, 0xffff0000, v119
	v_pk_add_f32 v[22:23], v[22:23], v[24:25]
	v_cvt_pk_bf16_f32 v20, v20, v21
	v_cvt_pk_bf16_f32 v21, v22, v23
	v_lshlrev_b32_e32 v22, 16, v120
	v_and_b32_e32 v23, 0xffff0000, v120
	v_pk_add_f32 v[16:17], v[16:17], v[22:23]
	s_nop 0
	v_cvt_pk_bf16_f32 v22, v16, v17
	v_lshlrev_b32_e32 v16, 16, v121
	v_and_b32_e32 v17, 0xffff0000, v121
	v_pk_add_f32 v[16:17], v[18:19], v[16:17]
	v_and_b32_e32 v18, 0xffff0000, v21
	v_cvt_pk_bf16_f32 v23, v16, v17
	v_and_b32_e32 v17, 0xffff0000, v20
	v_lshlrev_b32_e32 v16, 16, v20
	v_mul_f32_e32 v17, v17, v17
	v_fmac_f32_e32 v17, v16, v16
	v_add_f32_e32 v16, v17, v26
	v_lshlrev_b32_e32 v17, 16, v21
	v_mul_f32_e32 v18, v18, v18
	v_fmac_f32_e32 v18, v17, v17
	v_add_f32_e32 v16, v18, v16
	v_and_b32_e32 v18, 0xffff0000, v22
	v_lshlrev_b32_e32 v17, 16, v22
	v_mul_f32_e32 v18, v18, v18
	v_fmac_f32_e32 v18, v17, v17
	v_add_f32_e32 v16, v18, v16
	v_and_b32_e32 v18, 0xffff0000, v23
	v_lshlrev_b32_e32 v17, 16, v23
	v_mul_f32_e32 v18, v18, v18
	v_fmac_f32_e32 v18, v17, v17
	v_add_f32_e32 v16, v18, v16
	ds_bpermute_b32 v17, v235, v16
	v_lshl_add_u64 v[18:19], v[214:215], 0, s[0:1]
	s_mov_b64 s[0:1], 0xa0100
	v_lshl_add_u64 v[24:25], v[214:215], 0, s[0:1]
	global_store_dwordx4 v[18:19], v[28:31], off sc1
	global_store_dwordx4 v[24:25], v[20:23], off sc1
	s_waitcnt lgkmcnt(0)
	v_add_f32_e32 v16, v16, v17
	ds_bpermute_b32 v17, v236, v16
	s_and_saveexec_b64 s[0:1], s[38:39]
	s_cbranch_execz .LBB0_464
	v_add_u32_e32 v18, 0xa0, v212
	v_ashrrev_i32_e32 v19, 31, v18
	s_waitcnt lgkmcnt(0)
	v_add_f32_e32 v20, v16, v17
	v_lshlrev_b64 v[16:17], 7, v[18:19]
	v_lshl_add_u64 v[16:17], s[44:45], 0, v[16:17]
	v_lshl_add_u64 v[16:17], s[66:67], 2, v[16:17]
	s_lshl_b32 s28, s47, 2
	v_lshl_add_u64 v[16:17], v[16:17], 0, s[28:29]
	global_store_dword v[16:17], v20, off sc1
.LBB0_464:
	s_or_b64 exec, exec, s[0:1]
	v_lshlrev_b32_e32 v16, 16, v106
	s_waitcnt lgkmcnt(0)
	v_and_b32_e32 v17, 0xffff0000, v106
	v_pk_add_f32 v[12:13], v[12:13], v[16:17]
	v_lshlrev_b32_e32 v16, 16, v107
	v_and_b32_e32 v17, 0xffff0000, v107
	v_pk_add_f32 v[14:15], v[14:15], v[16:17]
	v_cvt_pk_bf16_f32 v12, v12, v13
	v_cvt_pk_bf16_f32 v13, v14, v15
	v_lshlrev_b32_e32 v14, 16, v108
	v_and_b32_e32 v15, 0xffff0000, v108
	v_pk_add_f32 v[8:9], v[8:9], v[14:15]
	s_mov_b64 s[0:1], 0xb0000
	v_cvt_pk_bf16_f32 v14, v8, v9
	v_lshlrev_b32_e32 v8, 16, v109
	v_and_b32_e32 v9, 0xffff0000, v109
	v_pk_add_f32 v[8:9], v[10:11], v[8:9]
	v_and_b32_e32 v10, 0xffff0000, v13
	v_cvt_pk_bf16_f32 v15, v8, v9
	v_and_b32_e32 v9, 0xffff0000, v12
	v_lshlrev_b32_e32 v8, 16, v12
	v_mul_f32_e32 v9, v9, v9
	v_fmac_f32_e32 v9, v8, v8
	v_lshlrev_b32_e32 v8, 16, v13
	v_mul_f32_e32 v10, v10, v10
	v_fmac_f32_e32 v10, v8, v8
	v_add_f32_e32 v8, v9, v10
	v_and_b32_e32 v10, 0xffff0000, v14
	v_lshlrev_b32_e32 v9, 16, v14
	v_mul_f32_e32 v10, v10, v10
	v_fmac_f32_e32 v10, v9, v9
	v_add_f32_e32 v8, v10, v8
	v_and_b32_e32 v10, 0xffff0000, v15
	v_lshlrev_b32_e32 v9, 16, v15
	v_mul_f32_e32 v10, v10, v10
	v_fmac_f32_e32 v10, v9, v9
	v_add_f32_e32 v10, v10, v8
	v_lshlrev_b32_e32 v8, 16, v98
	v_and_b32_e32 v9, 0xffff0000, v98
	v_pk_add_f32 v[4:5], v[4:5], v[8:9]
	v_lshlrev_b32_e32 v8, 16, v99
	v_and_b32_e32 v9, 0xffff0000, v99
	v_pk_add_f32 v[6:7], v[6:7], v[8:9]
	v_cvt_pk_bf16_f32 v4, v4, v5
	v_cvt_pk_bf16_f32 v5, v6, v7
	v_lshlrev_b32_e32 v6, 16, v100
	v_and_b32_e32 v7, 0xffff0000, v100
	v_pk_add_f32 v[0:1], v[0:1], v[6:7]
	s_nop 0
	v_cvt_pk_bf16_f32 v6, v0, v1
	v_lshlrev_b32_e32 v0, 16, v101
	v_and_b32_e32 v1, 0xffff0000, v101
	v_pk_add_f32 v[0:1], v[2:3], v[0:1]
	v_and_b32_e32 v2, 0xffff0000, v5
	v_cvt_pk_bf16_f32 v7, v0, v1
	v_and_b32_e32 v1, 0xffff0000, v4
	v_lshlrev_b32_e32 v0, 16, v4
	v_mul_f32_e32 v1, v1, v1
	v_fmac_f32_e32 v1, v0, v0
	v_add_f32_e32 v0, v1, v10
	v_lshlrev_b32_e32 v1, 16, v5
	v_mul_f32_e32 v2, v2, v2
	v_fmac_f32_e32 v2, v1, v1
	v_add_f32_e32 v0, v2, v0
	v_and_b32_e32 v2, 0xffff0000, v6
	v_lshlrev_b32_e32 v1, 16, v6
	v_mul_f32_e32 v2, v2, v2
	v_fmac_f32_e32 v2, v1, v1
	v_add_f32_e32 v0, v2, v0
	v_and_b32_e32 v2, 0xffff0000, v7
	v_lshlrev_b32_e32 v1, 16, v7
	v_mul_f32_e32 v2, v2, v2
	v_fmac_f32_e32 v2, v1, v1
	v_add_f32_e32 v0, v2, v0
	ds_bpermute_b32 v1, v235, v0
	v_lshl_add_u64 v[2:3], v[214:215], 0, s[0:1]
	s_mov_b64 s[0:1], 0xb0100
	v_lshl_add_u64 v[8:9], v[214:215], 0, s[0:1]
	global_store_dwordx4 v[2:3], v[12:15], off sc1
	global_store_dwordx4 v[8:9], v[4:7], off sc1
	s_waitcnt lgkmcnt(0)
	v_add_f32_e32 v0, v0, v1
	ds_bpermute_b32 v1, v236, v0
	s_and_saveexec_b64 s[0:1], s[38:39]
	s_cbranch_execz .LBB0_466
	v_add_u32_e32 v2, 0xb0, v212
	v_ashrrev_i32_e32 v3, 31, v2
	s_waitcnt lgkmcnt(0)
	v_add_f32_e32 v4, v0, v1
	v_lshlrev_b64 v[0:1], 7, v[2:3]
	v_lshl_add_u64 v[0:1], s[44:45], 0, v[0:1]
	v_lshl_add_u64 v[0:1], s[66:67], 2, v[0:1]
	s_lshl_b32 s28, s47, 2
	v_lshl_add_u64 v[0:1], v[0:1], 0, s[28:29]
	global_store_dword v[0:1], v4, off sc1

; __device__ __forceinline__ unsigned pk_bf16(float lo, float hi) { f32x2e v = {lo, hi}; bf16x2e b = __builtin_convertvector(v, bf16x2e); return __builtin_bit_cast(unsigned, b); }
;     __device__ __forceinline__ void operator()(const f32x4 (&acc)[2][2][4][2], const Unit& u, int wr, int wc, int fr, int fq) const {
;         const int row0 = u.pm * BM + wr * 64 + fr; const int col0 = u.pn * BM + wc * 32 + 8 * fq;
;     ...
;             for (int m = 0; m < 4; ++m) { bf16_t* rowp = O + (size_t)(row0 + ai * HALF + m * 16) * ldc + col0;
;                 const float rs = rsa[ai][m];
; #pragma unroll
;                 for (int bj = 0; bj < 2; ++bj) { const f32x4 v0 = acc[ai][bj][m][0] * rs, v1 = acc[ai][bj][m][1] * rs;
;                     u32x4 w; w.x = pk_bf16(v0[0], v0[1]); w.y = pk_bf16(v0[2], v0[3]); w.z = pk_bf16(v1[0], v1[1]); w.w = pk_bf16(v1[2], v1[3]);
;                     *(u32x4*)(rowp + bj * HALF) = w; } }
.LBB0_516:
	v_or_b32_e32 v131, s0, v191
	s_ashr_i32 s0, s0, 31
	v_lshl_or_b32 v134, s31, 8, v206
	v_mul_lo_u32 v133, s67, v131
	s_mul_i32 s31, s66, s0
	v_mad_u64_u32 v[136:137], s[0:1], s66, v131, 0
	v_ashrrev_i32_e32 v135, 31, v134
	v_add3_u32 v137, v137, s31, v133
	v_lshl_add_u64 v[136:137], v[136:137], 1, s[74:75]
	v_lshlrev_b64 v[134:135], 1, v[134:135]
	v_pk_mul_f32 v[128:129], v[128:129], v[192:193] op_sel_hi:[1,0]
	v_pk_mul_f32 v[126:127], v[126:127], v[192:193] op_sel_hi:[1,0]
	v_pk_mul_f32 v[138:139], v[124:125], v[192:193] op_sel_hi:[1,0]
	v_pk_mul_f32 v[124:125], v[122:123], v[192:193] op_sel_hi:[1,0]
	v_lshl_add_u64 v[136:137], v[136:137], 0, v[134:135]
	v_cvt_pk_bf16_f32 v122, v126, v127
	v_cvt_pk_bf16_f32 v123, v128, v129
	v_cvt_pk_bf16_f32 v124, v124, v125
	v_cvt_pk_bf16_f32 v125, v138, v139
	global_store_dwordx4 v[136:137], v[122:125], off sc1
	v_pk_mul_f32 v[120:121], v[120:121], v[192:193] op_sel_hi:[1,0]
	v_pk_mul_f32 v[118:119], v[118:119], v[192:193] op_sel_hi:[1,0]
	v_pk_mul_f32 v[122:123], v[112:113], v[192:193] op_sel_hi:[1,0]
	v_pk_mul_f32 v[112:113], v[110:111], v[192:193] op_sel_hi:[1,0]
	v_cvt_pk_bf16_f32 v110, v118, v119
	v_cvt_pk_bf16_f32 v111, v120, v121
	v_cvt_pk_bf16_f32 v112, v112, v113
	v_cvt_pk_bf16_f32 v113, v122, v123
	global_store_dwordx4 v[136:137], v[110:113], off offset:256 sc1
	s_waitcnt lgkmcnt(0)
	v_pk_mul_f32 v[114:115], v[114:115], v[190:191] op_sel_hi:[1,0]
	v_pk_mul_f32 v[104:105], v[104:105], v[190:191] op_sel_hi:[1,0]
	v_or_b32_e32 v110, 16, v131
	v_mul_lo_u32 v112, s67, v110
	v_mad_u64_u32 v[110:111], s[0:1], s66, v110, 0
	v_add3_u32 v111, v111, s31, v112
	v_lshl_add_u64 v[110:111], v[110:111], 1, s[74:75]
	v_pk_mul_f32 v[112:113], v[116:117], v[190:191] op_sel_hi:[1,0]
	v_pk_mul_f32 v[116:117], v[108:109], v[190:191] op_sel_hi:[1,0]
	v_pk_mul_f32 v[108:109], v[106:107], v[190:191] op_sel_hi:[1,0]
	v_lshl_add_u64 v[110:111], v[110:111], 0, v[134:135]
	v_cvt_pk_bf16_f32 v106, v114, v115
	v_cvt_pk_bf16_f32 v107, v112, v113
	v_cvt_pk_bf16_f32 v108, v108, v109
	v_cvt_pk_bf16_f32 v109, v116, v117
	global_store_dwordx4 v[110:111], v[106:109], off sc1
	v_pk_mul_f32 v[102:103], v[102:103], v[190:191] op_sel_hi:[1,0]
	v_pk_mul_f32 v[98:99], v[98:99], v[164:165] op_sel_hi:[1,0]
	v_pk_mul_f32 v[106:107], v[94:95], v[190:191] op_sel_hi:[1,0]
	v_pk_mul_f32 v[94:95], v[92:93], v[190:191] op_sel_hi:[1,0]
	v_cvt_pk_bf16_f32 v92, v102, v103
	v_cvt_pk_bf16_f32 v93, v104, v105
	v_cvt_pk_bf16_f32 v94, v94, v95
	v_cvt_pk_bf16_f32 v95, v106, v107
	global_store_dwordx4 v[110:111], v[92:95], off offset:256 sc1
	v_pk_mul_f32 v[86:87], v[86:87], v[164:165] op_sel_hi:[1,0]
	v_pk_mul_f32 v[84:85], v[84:85], v[164:165] op_sel_hi:[1,0]
	v_or_b32_e32 v92, 32, v131
	v_mul_lo_u32 v94, s67, v92
	v_mad_u64_u32 v[92:93], s[0:1], s66, v92, 0
	v_add3_u32 v93, v93, s31, v94
	v_lshl_add_u64 v[92:93], v[92:93], 1, s[74:75]
	v_pk_mul_f32 v[94:95], v[100:101], v[164:165] op_sel_hi:[1,0]
	v_pk_mul_f32 v[100:101], v[90:91], v[164:165] op_sel_hi:[1,0]
	v_pk_mul_f32 v[90:91], v[88:89], v[164:165] op_sel_hi:[1,0]
	v_lshl_add_u64 v[92:93], v[92:93], 0, v[134:135]
	v_cvt_pk_bf16_f32 v88, v98, v99
	v_cvt_pk_bf16_f32 v89, v94, v95
	v_cvt_pk_bf16_f32 v90, v90, v91
	v_cvt_pk_bf16_f32 v91, v100, v101
	global_store_dwordx4 v[92:93], v[88:91], off sc1
	v_pk_mul_f32 v[80:81], v[80:81], v[162:163] op_sel_hi:[1,0]
	v_pk_mul_f32 v[70:71], v[70:71], v[162:163] op_sel_hi:[1,0]
	v_pk_mul_f32 v[88:89], v[78:79], v[164:165] op_sel_hi:[1,0]
	v_pk_mul_f32 v[78:79], v[76:77], v[164:165] op_sel_hi:[1,0]
	v_cvt_pk_bf16_f32 v76, v84, v85
	v_cvt_pk_bf16_f32 v77, v86, v87
	v_cvt_pk_bf16_f32 v78, v78, v79
	v_cvt_pk_bf16_f32 v79, v88, v89
	global_store_dwordx4 v[92:93], v[76:79], off offset:256 sc1
	v_pk_mul_f32 v[68:69], v[68:69], v[162:163] op_sel_hi:[1,0]
	v_pk_mul_f32 v[62:63], v[62:63], v[148:149] op_sel_hi:[1,0]
	v_or_b32_e32 v76, 48, v131
	v_mul_lo_u32 v78, s67, v76
	v_mad_u64_u32 v[76:77], s[0:1], s66, v76, 0
	v_add3_u32 v77, v77, s31, v78
	v_lshl_add_u64 v[76:77], v[76:77], 1, s[74:75]
	v_pk_mul_f32 v[78:79], v[82:83], v[162:163] op_sel_hi:[1,0]
	v_pk_mul_f32 v[82:83], v[74:75], v[162:163] op_sel_hi:[1,0]
	v_pk_mul_f32 v[74:75], v[72:73], v[162:163] op_sel_hi:[1,0]
	v_lshl_add_u64 v[76:77], v[76:77], 0, v[134:135]
	v_cvt_pk_bf16_f32 v72, v80, v81
	v_cvt_pk_bf16_f32 v73, v78, v79
	v_cvt_pk_bf16_f32 v74, v74, v75
	v_cvt_pk_bf16_f32 v75, v82, v83
	global_store_dwordx4 v[76:77], v[72:75], off sc1
	v_pk_mul_f32 v[60:61], v[60:61], v[148:149] op_sel_hi:[1,0]
	v_pk_mul_f32 v[54:55], v[54:55], v[148:149] op_sel_hi:[1,0]
	v_pk_mul_f32 v[72:73], v[66:67], v[162:163] op_sel_hi:[1,0]
	v_pk_mul_f32 v[66:67], v[64:65], v[162:163] op_sel_hi:[1,0]
	v_cvt_pk_bf16_f32 v64, v68, v69
; __device__ __forceinline__ unsigned pk_bf16(float lo, float hi) { f32x2e v = {lo, hi}; bf16x2e b = __builtin_convertvector(v, bf16x2e); return __builtin_bit_cast(unsigned, b); }
; #define PG8_BAR __builtin_amdgcn_s_barrier()
;     __device__ __forceinline__ void operator()(const f32x4 (&acc)[2][2][4][2], const Unit& u, int wr, int wc, int fr, int fq) const {
;     ...
;             for (int m = 0; m < 4; ++m) { bf16_t* rowp = O + (size_t)(row0 + ai * HALF + m * 16) * ldc + col0;
;                 const float rs = rsa[ai][m];
; #pragma unroll
;                 for (int bj = 0; bj < 2; ++bj) { const f32x4 v0 = acc[ai][bj][m][0] * rs, v1 = acc[ai][bj][m][1] * rs;
;                     u32x4 w; w.x = pk_bf16(v0[0], v0[1]); w.y = pk_bf16(v0[2], v0[3]); w.z = pk_bf16(v1[0], v1[1]); w.w = pk_bf16(v1[2], v1[3]);
;                     *(u32x4*)(rowp + bj * HALF) = w; } }
; template <class Epi, class Sched, bool ALIGN_EPI = false, bool SP2 = false>
; __device__ __forceinline__ void gemm_phase(PG8_LAS unsigned char* lds, const Gemm g, const Sched& S, const Epi& E) {
;     ...
;         if (!has_next) break;
; #pragma unroll
;         for (int a = 0; a < 2; ++a)
; #pragma unroll
;             for (int b = 0; b < 2; ++b)
; #pragma unroll
;                 for (int m = 0; m < 4; ++m)
; #pragma unroll
;                     for (int n = 0; n < 2; ++n) acc[a][b][m][n] = (f32x4){0.f, 0.f, 0.f, 0.f};
;         cur = nxt; cA = nA; cB = nB; ++ui;
;         if constexpr (ALIGN_EPI) { if (wr == 1) PG8_BAR; }
	v_cvt_pk_bf16_f32 v65, v70, v71
	v_cvt_pk_bf16_f32 v66, v66, v67
	v_cvt_pk_bf16_f32 v67, v72, v73
	global_store_dwordx4 v[76:77], v[64:67], off offset:256 sc1
	v_pk_mul_f32 v[52:53], v[52:53], v[148:149] op_sel_hi:[1,0]
	v_pk_mul_f32 v[48:49], v[48:49], v[146:147] op_sel_hi:[1,0]
	v_add_u32_e32 v64, 0x80, v131
	v_ashrrev_i32_e32 v65, 31, v64
	v_mul_lo_u32 v66, s66, v65
	v_mul_lo_u32 v67, s67, v64
	v_mad_u64_u32 v[64:65], s[0:1], s66, v64, 0
	v_add3_u32 v65, v65, v66, v67
	v_lshl_add_u64 v[64:65], v[64:65], 1, s[74:75]
	v_pk_mul_f32 v[66:67], v[58:59], v[148:149] op_sel_hi:[1,0]
	v_pk_mul_f32 v[58:59], v[56:57], v[148:149] op_sel_hi:[1,0]
	v_lshl_add_u64 v[64:65], v[64:65], 0, v[134:135]
	v_cvt_pk_bf16_f32 v56, v60, v61
	v_cvt_pk_bf16_f32 v57, v62, v63
	v_cvt_pk_bf16_f32 v58, v58, v59
	v_cvt_pk_bf16_f32 v59, v66, v67
	global_store_dwordx4 v[64:65], v[56:59], off sc1
	v_pk_mul_f32 v[38:39], v[38:39], v[146:147] op_sel_hi:[1,0]
	v_pk_mul_f32 v[36:37], v[36:37], v[146:147] op_sel_hi:[1,0]
	v_pk_mul_f32 v[56:57], v[46:47], v[148:149] op_sel_hi:[1,0]
	v_pk_mul_f32 v[46:47], v[44:45], v[148:149] op_sel_hi:[1,0]
	v_cvt_pk_bf16_f32 v44, v52, v53
	v_cvt_pk_bf16_f32 v45, v54, v55
	v_cvt_pk_bf16_f32 v46, v46, v47
	v_cvt_pk_bf16_f32 v47, v56, v57
	global_store_dwordx4 v[64:65], v[44:47], off offset:256 sc1
	v_pk_mul_f32 v[32:33], v[32:33], v[132:133] op_sel_hi:[1,0]
	v_pk_mul_f32 v[22:23], v[22:23], v[132:133] op_sel_hi:[1,0]
	v_add_u32_e32 v44, 0x90, v131
	v_ashrrev_i32_e32 v45, 31, v44
	v_mul_lo_u32 v46, s66, v45
	v_mul_lo_u32 v47, s67, v44
	v_mad_u64_u32 v[44:45], s[0:1], s66, v44, 0
	v_add3_u32 v45, v45, v46, v47
	v_lshl_add_u64 v[44:45], v[44:45], 1, s[74:75]
	v_pk_mul_f32 v[46:47], v[50:51], v[146:147] op_sel_hi:[1,0]
	v_pk_mul_f32 v[50:51], v[42:43], v[146:147] op_sel_hi:[1,0]
	v_pk_mul_f32 v[42:43], v[40:41], v[146:147] op_sel_hi:[1,0]
	v_lshl_add_u64 v[44:45], v[44:45], 0, v[134:135]
	v_cvt_pk_bf16_f32 v40, v48, v49
	v_cvt_pk_bf16_f32 v41, v46, v47
	v_cvt_pk_bf16_f32 v42, v42, v43
	v_cvt_pk_bf16_f32 v43, v50, v51
	global_store_dwordx4 v[44:45], v[40:43], off sc1
	v_pk_mul_f32 v[20:21], v[20:21], v[132:133] op_sel_hi:[1,0]
	v_pk_mul_f32 v[16:17], v[16:17], v[130:131] op_sel_hi:[1,0]
	v_pk_mul_f32 v[40:41], v[30:31], v[146:147] op_sel_hi:[1,0]
	v_pk_mul_f32 v[30:31], v[28:29], v[146:147] op_sel_hi:[1,0]
	v_cvt_pk_bf16_f32 v28, v36, v37
	v_cvt_pk_bf16_f32 v29, v38, v39
	v_cvt_pk_bf16_f32 v30, v30, v31
	v_cvt_pk_bf16_f32 v31, v40, v41
	global_store_dwordx4 v[44:45], v[28:31], off offset:256 sc1
	v_pk_mul_f32 v[6:7], v[6:7], v[130:131] op_sel_hi:[1,0]
	v_pk_mul_f32 v[4:5], v[4:5], v[130:131] op_sel_hi:[1,0]
	v_add_u32_e32 v28, 0xa0, v131
	v_ashrrev_i32_e32 v29, 31, v28
	v_mul_lo_u32 v30, s66, v29
	v_mul_lo_u32 v31, s67, v28
	v_mad_u64_u32 v[28:29], s[0:1], s66, v28, 0
	v_add3_u32 v29, v29, v30, v31
	v_lshl_add_u64 v[28:29], v[28:29], 1, s[74:75]
	v_pk_mul_f32 v[30:31], v[34:35], v[132:133] op_sel_hi:[1,0]
	v_pk_mul_f32 v[34:35], v[26:27], v[132:133] op_sel_hi:[1,0]
	v_pk_mul_f32 v[26:27], v[24:25], v[132:133] op_sel_hi:[1,0]
	v_lshl_add_u64 v[28:29], v[28:29], 0, v[134:135]
	v_cvt_pk_bf16_f32 v24, v32, v33
	v_cvt_pk_bf16_f32 v25, v30, v31
	v_cvt_pk_bf16_f32 v26, v26, v27
	v_cvt_pk_bf16_f32 v27, v34, v35
	global_store_dwordx4 v[28:29], v[24:27], off sc1
	s_and_b64 vcc, exec, s[38:39]
	s_nop 0
	v_pk_mul_f32 v[24:25], v[14:15], v[132:133] op_sel_hi:[1,0]
	v_pk_mul_f32 v[14:15], v[12:13], v[132:133] op_sel_hi:[1,0]
	v_cvt_pk_bf16_f32 v12, v20, v21
	v_cvt_pk_bf16_f32 v13, v22, v23
	v_cvt_pk_bf16_f32 v14, v14, v15
	v_cvt_pk_bf16_f32 v15, v24, v25
	global_store_dwordx4 v[28:29], v[12:15], off offset:256 sc1
	s_nop 1
	v_add_u32_e32 v12, 0xb0, v131
	v_ashrrev_i32_e32 v13, 31, v12
	v_mul_lo_u32 v14, s66, v13
	v_mul_lo_u32 v15, s67, v12
	v_mad_u64_u32 v[12:13], s[0:1], s66, v12, 0
	v_add3_u32 v13, v13, v14, v15
	v_lshl_add_u64 v[12:13], v[12:13], 1, s[74:75]
	v_pk_mul_f32 v[14:15], v[18:19], v[130:131] op_sel_hi:[1,0]
	v_pk_mul_f32 v[18:19], v[10:11], v[130:131] op_sel_hi:[1,0]
	v_pk_mul_f32 v[10:11], v[8:9], v[130:131] op_sel_hi:[1,0]
	v_lshl_add_u64 v[12:13], v[12:13], 0, v[134:135]
	v_cvt_pk_bf16_f32 v8, v16, v17
	v_cvt_pk_bf16_f32 v9, v14, v15
	v_cvt_pk_bf16_f32 v10, v10, v11
	v_cvt_pk_bf16_f32 v11, v18, v19
	global_store_dwordx4 v[12:13], v[8:11], off sc1
	s_mov_b64 s[0:1], -1
	s_nop 0
	v_pk_mul_f32 v[8:9], v[2:3], v[130:131] op_sel_hi:[1,0]
	v_pk_mul_f32 v[2:3], v[0:1], v[130:131] op_sel_hi:[1,0]
	v_cvt_pk_bf16_f32 v0, v4, v5
	v_cvt_pk_bf16_f32 v1, v6, v7
	v_cvt_pk_bf16_f32 v2, v2, v3
	v_cvt_pk_bf16_f32 v3, v8, v9
	global_store_dwordx4 v[12:13], v[0:3], off offset:256 sc1
	s_cbranch_vccnz .LBB0_502
	s_andn2_b64 vcc, exec, s[80:81]
	s_cbranch_vccnz .LBB0_501
	s_barrier
	s_branch .LBB0_501
